# fused GEMM epilogues (w_out, mlp_out): the 16 serialized residual-tile loads per wave are issued ahead (7 before the RMS exchange, 9 into already-consumed accumulator registers) with counted vmcnt wai
# speedup vs baseline: 1.0267x; 1.0097x over previous
; __device__ __forceinline__ void panel_rms(const f32x4 (&v)[2][2][4][2], int pm, int pn, int wr, int wc, int fr, int fq, LAS unsigned char* xl, int wid, int lane, float* slots, unsigned* cnt) {
;     ...
; #pragma unroll
;     for (int ai = 0; ai < 2; ++ai)
; #pragma unroll
;         for (int m = 0; m < 4; ++m) { float q = 0.f;
; #pragma unroll
;             for (int bj = 0; bj < 2; ++bj)
; #pragma unroll
;                 for (int n = 0; n < 2; ++n) { const f32x4 x = v[ai][bj][m][n]; q += (x[0] * x[0] + x[1] * x[1]) + (x[2] * x[2] + x[3] * x[3]); }
;             q += __shfl_xor(q, 16); q += __shfl_xor(q, 32);
;             if (fq == 0) P[(ai * HALF + wr * 64 + m * 16 + fr) * 4 + wc] = q; }
; __device__ __forceinline__ void fused_epi(f32x4 (&acc)[2][2][4][2], const Unit& u, int wr, int wc, int fr, int fq, LAS unsigned char* xl, int wid, int lane, const FuseArgs& f) {
;     ...
;                 for (int bj = 0; bj < 2; ++bj) { const size_t off = (size_t)(pm * BM + r) * DM + colb + bj * HALF;
;                     const u32x4 xw = *(const u32x4*)((const bf16_t*)(f.ws + WS_XR) + off);
.LBB0_63:
	s_lshl_b32 s32, s53, 19
	s_add_u32 s34, s78, s32
	s_addc_u32 s35, s79, 0
	s_lshl_b32 s32, s22, 9
	s_add_u32 s34, s34, s32
	s_addc_u32 s35, s35, 0
	v_lshlrev_b32_e32 v217, 11, v167
	v_lshl_add_u32 v217, v213, 1, v217
	global_load_dwordx4 v[224:227], v217, s[34:35]
	global_load_dwordx4 v[228:231], v217, s[34:35] offset:256
	v_lshlrev_b32_e32 v217, 11, v198
	v_lshl_add_u32 v217, v213, 1, v217
	global_load_dwordx4 v[232:235], v217, s[34:35]
	global_load_dwordx4 v[236:239], v217, s[34:35] offset:256
	v_lshlrev_b32_e32 v217, 11, v200
	v_lshl_add_u32 v217, v213, 1, v217
	global_load_dwordx4 v[240:243], v217, s[34:35]
	global_load_dwordx4 v[244:247], v217, s[34:35] offset:256
	v_lshlrev_b32_e32 v217, 11, v202
	v_lshl_add_u32 v217, v213, 1, v217
	global_load_dwordx4 v[248:251], v217, s[34:35]
	v_mul_f32_e32 v130, v125, v125
	v_mul_f32_e32 v131, v127, v127
	v_fmac_f32_e32 v130, v124, v124
	v_fmac_f32_e32 v131, v126, v126
	v_add_f32_e32 v130, v130, v131
	v_mul_f32_e32 v131, v121, v121
	v_mul_f32_e32 v132, v123, v123
	v_fmac_f32_e32 v131, v120, v120
	v_fmac_f32_e32 v132, v122, v122
	v_add_f32_e32 v131, v131, v132
	v_add_f32_e32 v130, v130, v131
	v_mul_f32_e32 v131, v105, v105
	v_mul_f32_e32 v132, v107, v107
	v_fmac_f32_e32 v131, v104, v104
	v_fmac_f32_e32 v132, v106, v106
	v_and_b32_e32 v129, 64, v221
	v_add_f32_e32 v131, v131, v132
	v_xor_b32_e32 v128, 16, v221
	v_add_u32_e32 v129, 64, v129
	v_add_f32_e32 v130, v130, v131
	v_mul_f32_e32 v131, v97, v97
	v_mul_f32_e32 v132, v99, v99
	v_cmp_lt_i32_e32 vcc, v128, v129
	v_fmac_f32_e32 v131, v96, v96
	v_fmac_f32_e32 v132, v98, v98
	v_cndmask_b32_e32 v128, v221, v128, vcc
	v_add_f32_e32 v131, v131, v132
	v_lshlrev_b32_e32 v128, 2, v128
	v_add_f32_e32 v130, v130, v131
	ds_bpermute_b32 v131, v128, v130
	v_xor_b32_e32 v132, 32, v221
	v_cmp_lt_i32_e32 vcc, v132, v129
	s_waitcnt lgkmcnt(0)
	v_add_f32_e32 v130, v130, v131
	v_cndmask_b32_e32 v129, v221, v132, vcc
	v_lshlrev_b32_e32 v129, 2, v129
	ds_bpermute_b32 v131, v129, v130
	s_and_saveexec_b64 s[12:13], s[4:5]
	s_cbranch_execz .LBB0_65
	s_waitcnt lgkmcnt(0)
	v_add_f32_e32 v130, v130, v131
	ds_write_b32 v216, v130

; __device__ __forceinline__ f32x4 bfx4_lo(u32x4 w) { return (f32x4){bf_lo(w.x), bf_hi(w.x), bf_lo(w.y), bf_hi(w.y)}; }
; __device__ __forceinline__ f32x4 bfx4_hi(u32x4 w) { return (f32x4){bf_lo(w.z), bf_hi(w.z), bf_lo(w.w), bf_hi(w.w)}; }
; __device__ __forceinline__ void fused_epi(f32x4 (&acc)[2][2][4][2], const Unit& u, int wr, int wc, int fr, int fq, LAS unsigned char* xl, int wid, int lane, const FuseArgs& f) {
;     ...
;         for (int bj = 0; bj < 2; ++bj)
; #pragma unroll
;             for (int n = 0; n < 2; ++n) { const int c = colb + bj * HALF + 4 * n; Gv[bj][n] = *(const f32x4*)(f.modl + f.gate_off + mrow + c) * *(const f32x4*)(f.gpost + c); }
; #pragma unroll
;         for (int ai = 0; ai < 2; ++ai)
; #pragma unroll
;             for (int m = 0; m < 4; ++m) { const int r = ai * HALF + wr * 64 + m * 16 + fr; const float rstd = S[r];
; #pragma unroll
;                 for (int bj = 0; bj < 2; ++bj) { const size_t off = (size_t)(pm * BM + r) * DM + colb + bj * HALF;
;                     const u32x4 xw = *(const u32x4*)((const bf16_t*)(f.ws + WS_XR) + off);
;                     const f32x4 x0 = bfx4_lo(xw) + Gv[bj][0] * (acc[ai][bj][m][0] * rstd), x1 = bfx4_hi(xw) + Gv[bj][1] * (acc[ai][bj][m][1] * rstd);
;                     if (f.out_f32) { *(f32x4*)(f.xoutf + off) = x0; *(f32x4*)(f.xoutf + off + 4) = x1; acc[ai][bj][m][0] = x0; acc[ai][bj][m][1] = x1; }
.LBB0_100:
	s_or_b64 exec, exec, s[12:13]
	s_ashr_i32 s12, s53, 4
	v_lshl_or_b32 v176, s22, 8, v213
	s_mul_hi_i32 s13, s12, 0x6000
	s_mulk_i32 s12, 0x6000
	v_readlane_b32 s21, v255, 33
	s_add_u32 s12, s21, s12
	v_readlane_b32 s21, v255, 34
	v_ashrrev_i32_e32 v177, 31, v176
	s_addc_u32 s13, s21, s13
	v_lshlrev_b64 v[136:137], 2, v[176:177]
	s_waitcnt vmcnt(0) lgkmcnt(0)
	s_barrier
	v_lshl_add_u64 v[144:145], s[12:13], 0, v[136:137]
	v_lshl_add_u64 v[146:147], s[48:49], 0, v[136:137]
	global_load_dwordx4 v[128:131], v[144:145], off offset:16
	global_load_dwordx4 v[132:135], v[144:145], off
	global_load_dwordx4 v[136:139], v[146:147], off offset:16
	global_load_dwordx4 v[140:143], v[146:147], off
	s_mov_b64 s[68:69], -1
	s_andn2_b64 vcc, exec, s[16:17]
	s_waitcnt vmcnt(0)
	v_pk_mul_f32 v[178:179], v[130:131], v[138:139]
	v_pk_mul_f32 v[182:183], v[134:135], v[142:143]
	v_pk_mul_f32 v[184:185], v[132:133], v[140:141]
	v_pk_mul_f32 v[180:181], v[128:129], v[136:137]
	global_load_dwordx4 v[128:131], v[144:145], off offset:528
	global_load_dwordx4 v[136:139], v[144:145], off offset:512
	global_load_dwordx4 v[132:135], v[146:147], off offset:528
	global_load_dwordx4 v[140:143], v[146:147], off offset:512
	v_add_u32_e32 v144, s9, v167
	v_ashrrev_i32_e32 v145, 31, v144
	v_lshlrev_b64 v[144:145], 10, v[144:145]
	v_lshl_add_u64 v[188:189], v[144:145], 0, v[176:177]
	v_lshl_add_u64 v[192:193], v[188:189], 1, s[78:79]
	ds_read_b32 v186, v197
	s_waitcnt lgkmcnt(0)
	v_pk_mul_f32 v[150:151], v[126:127], v[186:187] op_sel_hi:[1,0]
	v_pk_mul_f32 v[160:161], v[124:125], v[186:187] op_sel_hi:[1,0]
	v_pk_mul_f32 v[190:191], v[120:121], v[186:187] op_sel_hi:[1,0]
	s_waitcnt vmcnt(0)
	s_nop 1
	v_mov_b32_e32 v146, v224
	v_mov_b32_e32 v147, v225
	v_mov_b32_e32 v148, v226
	v_mov_b32_e32 v149, v227
	v_lshlrev_b32_e32 v144, 16, v146
	v_and_b32_e32 v145, 0xffff0000, v146
	v_lshlrev_b32_e32 v146, 16, v147
	v_and_b32_e32 v147, 0xffff0000, v147
	v_pk_fma_f32 v[146:147], v[182:183], v[150:151], v[146:147]
	v_pk_fma_f32 v[144:145], v[184:185], v[160:161], v[144:145]
	v_lshlrev_b32_e32 v160, 16, v148
	v_and_b32_e32 v161, 0xffff0000, v148
	v_lshlrev_b32_e32 v148, 16, v149
	v_and_b32_e32 v149, 0xffff0000, v149
	v_pk_mul_f32 v[150:151], v[122:123], v[186:187] op_sel_hi:[1,0]
	s_nop 0
	v_pk_fma_f32 v[150:151], v[178:179], v[150:151], v[148:149]
	v_pk_fma_f32 v[148:149], v[180:181], v[190:191], v[160:161]
	v_cndmask_b32_e64 v160, 0, 1, s[16:17]
	v_cmp_ne_u32_e64 s[12:13], 1, v160
	v_lshl_add_u64 v[190:191], v[188:189], 2, s[42:43]
	s_cbranch_vccnz .LBB0_102
	s_mov_b64 s[68:69], 0
	global_store_dwordx4 v[190:191], v[144:147], off
	global_store_dwordx4 v[190:191], v[148:151], off offset:16

; __device__ __forceinline__ unsigned cvt_pk_bf16(float lo, float hi) { const f32x2 v = (f32x2){lo, hi}; return __builtin_bit_cast(unsigned, __builtin_convertvector(v, bf16v2)); }
; __device__ __forceinline__ f32x4 bfx4_lo(u32x4 w) { return (f32x4){bf_lo(w.x), bf_hi(w.x), bf_lo(w.y), bf_hi(w.y)}; }
; __device__ __forceinline__ f32x4 bfx4_hi(u32x4 w) { return (f32x4){bf_lo(w.z), bf_hi(w.z), bf_lo(w.w), bf_hi(w.w)}; }
; __device__ __forceinline__ void fused_epi(f32x4 (&acc)[2][2][4][2], const Unit& u, int wr, int wc, int fr, int fq, LAS unsigned char* xl, int wid, int lane, const FuseArgs& f) {
;     ...
;             for (int m = 0; m < 4; ++m) { const int r = ai * HALF + wr * 64 + m * 16 + fr; const float rstd = S[r];
; #pragma unroll
;                 for (int bj = 0; bj < 2; ++bj) { const size_t off = (size_t)(pm * BM + r) * DM + colb + bj * HALF;
;                     const u32x4 xw = *(const u32x4*)((const bf16_t*)(f.ws + WS_XR) + off);
;                     const f32x4 x0 = bfx4_lo(xw) + Gv[bj][0] * (acc[ai][bj][m][0] * rstd), x1 = bfx4_hi(xw) + Gv[bj][1] * (acc[ai][bj][m][1] * rstd);
;                     if (f.out_f32) { *(f32x4*)(f.xoutf + off) = x0; *(f32x4*)(f.xoutf + off + 4) = x1; acc[ai][bj][m][0] = x0; acc[ai][bj][m][1] = x1; }
;                     else { u32x4 w; w.x = cvt_pk_bf16(x0[0], x0[1]); w.y = cvt_pk_bf16(x0[2], x0[3]); w.z = cvt_pk_bf16(x1[0], x1[1]); w.w = cvt_pk_bf16(x1[2], x1[3]);
;                         *(u32x4*)((bf16_t*)(f.ws + WS_XR) + off) = w; acc[ai][bj][m][0] = bfx4_lo(w); acc[ai][bj][m][1] = bfx4_hi(w); } }
.LBB0_104:
	v_pk_mul_f32 v[138:139], v[138:139], v[142:143]
	v_pk_mul_f32 v[142:143], v[136:137], v[140:141]
	v_pk_mul_f32 v[140:141], v[128:129], v[132:133]
	v_lshlrev_b64 v[128:129], 1, v[188:189]
	v_or_b32_e32 v128, 0x100, v128
	v_lshl_add_u64 v[144:145], s[78:79], 0, v[128:129]
	v_pk_mul_f32 v[136:137], v[130:131], v[134:135]
	v_mov_b32_e32 v187, v186
	v_mov_b32_e32 v134, v186
	v_mov_b32_e32 v135, v186
	v_pk_mul_f32 v[146:147], v[106:107], v[134:135]
	v_pk_mul_f32 v[148:149], v[104:105], v[186:187]
	v_pk_mul_f32 v[134:135], v[98:99], v[134:135]
	s_mov_b64 s[68:69], -1
	s_and_b64 vcc, exec, s[12:13]
	s_nop 1
	v_mov_b32_e32 v130, v228
	v_mov_b32_e32 v131, v229
	v_mov_b32_e32 v132, v230
	v_mov_b32_e32 v133, v231
	v_lshlrev_b32_e32 v128, 16, v130
	v_and_b32_e32 v129, 0xffff0000, v130
	v_lshlrev_b32_e32 v130, 16, v131
	v_and_b32_e32 v131, 0xffff0000, v131
	v_pk_fma_f32 v[130:131], v[138:139], v[146:147], v[130:131]
	v_pk_fma_f32 v[128:129], v[142:143], v[148:149], v[128:129]
	v_lshlrev_b32_e32 v146, 16, v132
	v_and_b32_e32 v147, 0xffff0000, v132
	v_lshlrev_b32_e32 v132, 16, v133
	v_and_b32_e32 v133, 0xffff0000, v133
	v_pk_mul_f32 v[148:149], v[96:97], v[186:187]
	v_pk_fma_f32 v[134:135], v[136:137], v[134:135], v[132:133]
	v_pk_fma_f32 v[132:133], v[140:141], v[148:149], v[146:147]
	s_cbranch_vccnz .LBB0_106
	s_mov_b64 s[68:69], 0
	global_store_dwordx4 v[190:191], v[128:131], off offset:512
	global_store_dwordx4 v[190:191], v[132:135], off offset:528

; __device__ __forceinline__ unsigned cvt_pk_bf16(float lo, float hi) { const f32x2 v = (f32x2){lo, hi}; return __builtin_bit_cast(unsigned, __builtin_convertvector(v, bf16v2)); }
; __device__ __forceinline__ f32x4 bfx4_lo(u32x4 w) { return (f32x4){bf_lo(w.x), bf_hi(w.x), bf_lo(w.y), bf_hi(w.y)}; }
; __device__ __forceinline__ f32x4 bfx4_hi(u32x4 w) { return (f32x4){bf_lo(w.z), bf_hi(w.z), bf_lo(w.w), bf_hi(w.w)}; }
; __device__ __forceinline__ void fused_epi(f32x4 (&acc)[2][2][4][2], const Unit& u, int wr, int wc, int fr, int fq, LAS unsigned char* xl, int wid, int lane, const FuseArgs& f) {
;     ...
;             for (int m = 0; m < 4; ++m) { const int r = ai * HALF + wr * 64 + m * 16 + fr; const float rstd = S[r];
; #pragma unroll
;                 for (int bj = 0; bj < 2; ++bj) { const size_t off = (size_t)(pm * BM + r) * DM + colb + bj * HALF;
;                     const u32x4 xw = *(const u32x4*)((const bf16_t*)(f.ws + WS_XR) + off);
;                     const f32x4 x0 = bfx4_lo(xw) + Gv[bj][0] * (acc[ai][bj][m][0] * rstd), x1 = bfx4_hi(xw) + Gv[bj][1] * (acc[ai][bj][m][1] * rstd);
;                     if (f.out_f32) { *(f32x4*)(f.xoutf + off) = x0; *(f32x4*)(f.xoutf + off + 4) = x1; acc[ai][bj][m][0] = x0; acc[ai][bj][m][1] = x1; }
;                     else { u32x4 w; w.x = cvt_pk_bf16(x0[0], x0[1]); w.y = cvt_pk_bf16(x0[2], x0[3]); w.z = cvt_pk_bf16(x1[0], x1[1]); w.w = cvt_pk_bf16(x1[2], x1[3]);
;                         *(u32x4*)((bf16_t*)(f.ws + WS_XR) + off) = w; acc[ai][bj][m][0] = bfx4_lo(w); acc[ai][bj][m][1] = bfx4_hi(w); } }
.LBB0_108:
	v_lshlrev_b32_e32 v217, 11, v202
	v_lshl_add_u32 v217, v213, 1, v217
	global_load_dwordx4 v[120:123], v217, s[34:35] offset:256
	v_lshlrev_b32_e32 v217, 11, v204
	v_lshl_add_u32 v217, v213, 1, v217
	global_load_dwordx4 v[124:127], v217, s[34:35]
	global_load_dwordx4 v[96:99], v217, s[34:35] offset:256
	v_lshlrev_b32_e32 v217, 11, v206
	v_lshl_add_u32 v217, v213, 1, v217
	global_load_dwordx4 v[104:107], v217, s[34:35]
	s_nop 1
	v_add_u32_e32 v128, s9, v198
	v_ashrrev_i32_e32 v129, 31, v128
	v_lshlrev_b64 v[128:129], 10, v[128:129]
	v_lshl_add_u64 v[148:149], v[128:129], 0, v[176:177]
	v_lshl_add_u64 v[150:151], v[148:149], 1, s[78:79]
	ds_read_b32 v144, v199
	s_mov_b64 s[68:69], -1
	s_and_b64 vcc, exec, s[12:13]
	s_waitcnt lgkmcnt(0)
	v_pk_mul_f32 v[134:135], v[118:119], v[144:145] op_sel_hi:[1,0]
	v_pk_mul_f32 v[146:147], v[116:117], v[144:145] op_sel_hi:[1,0]
	v_pk_mul_f32 v[160:161], v[112:113], v[144:145] op_sel_hi:[1,0]
	s_nop 1
	v_mov_b32_e32 v130, v232
	v_mov_b32_e32 v131, v233
	v_mov_b32_e32 v132, v234
	v_mov_b32_e32 v133, v235
	v_lshlrev_b32_e32 v128, 16, v130
	v_and_b32_e32 v129, 0xffff0000, v130
	v_lshlrev_b32_e32 v130, 16, v131
	v_and_b32_e32 v131, 0xffff0000, v131
	v_pk_fma_f32 v[130:131], v[182:183], v[134:135], v[130:131]
	v_pk_fma_f32 v[128:129], v[184:185], v[146:147], v[128:129]
	v_lshlrev_b32_e32 v146, 16, v132
	v_and_b32_e32 v147, 0xffff0000, v132
	v_lshlrev_b32_e32 v132, 16, v133
	v_and_b32_e32 v133, 0xffff0000, v133
	v_pk_mul_f32 v[134:135], v[114:115], v[144:145] op_sel_hi:[1,0]
	s_nop 0
	v_pk_fma_f32 v[134:135], v[178:179], v[134:135], v[132:133]
	v_pk_fma_f32 v[132:133], v[180:181], v[160:161], v[146:147]
	v_lshl_add_u64 v[146:147], v[148:149], 2, s[42:43]
	s_cbranch_vccnz .LBB0_110
	s_mov_b64 s[68:69], 0
	global_store_dwordx4 v[146:147], v[128:131], off
	global_store_dwordx4 v[146:147], v[132:135], off offset:16

; __device__ __forceinline__ unsigned cvt_pk_bf16(float lo, float hi) { const f32x2 v = (f32x2){lo, hi}; return __builtin_bit_cast(unsigned, __builtin_convertvector(v, bf16v2)); }
; __device__ __forceinline__ f32x4 bfx4_lo(u32x4 w) { return (f32x4){bf_lo(w.x), bf_hi(w.x), bf_lo(w.y), bf_hi(w.y)}; }
; __device__ __forceinline__ f32x4 bfx4_hi(u32x4 w) { return (f32x4){bf_lo(w.z), bf_hi(w.z), bf_lo(w.w), bf_hi(w.w)}; }
; __device__ __forceinline__ void fused_epi(f32x4 (&acc)[2][2][4][2], const Unit& u, int wr, int wc, int fr, int fq, LAS unsigned char* xl, int wid, int lane, const FuseArgs& f) {
;     ...
;             for (int m = 0; m < 4; ++m) { const int r = ai * HALF + wr * 64 + m * 16 + fr; const float rstd = S[r];
; #pragma unroll
;                 for (int bj = 0; bj < 2; ++bj) { const size_t off = (size_t)(pm * BM + r) * DM + colb + bj * HALF;
;                     const u32x4 xw = *(const u32x4*)((const bf16_t*)(f.ws + WS_XR) + off);
;                     const f32x4 x0 = bfx4_lo(xw) + Gv[bj][0] * (acc[ai][bj][m][0] * rstd), x1 = bfx4_hi(xw) + Gv[bj][1] * (acc[ai][bj][m][1] * rstd);
;                     if (f.out_f32) { *(f32x4*)(f.xoutf + off) = x0; *(f32x4*)(f.xoutf + off + 4) = x1; acc[ai][bj][m][0] = x0; acc[ai][bj][m][1] = x1; }
;                     else { u32x4 w; w.x = cvt_pk_bf16(x0[0], x0[1]); w.y = cvt_pk_bf16(x0[2], x0[3]); w.z = cvt_pk_bf16(x1[0], x1[1]); w.w = cvt_pk_bf16(x1[2], x1[3]);
;                         *(u32x4*)((bf16_t*)(f.ws + WS_XR) + off) = w; acc[ai][bj][m][0] = bfx4_lo(w); acc[ai][bj][m][1] = bfx4_hi(w); } }
.LBB0_112:
	s_nop 1
	v_lshlrev_b64 v[128:129], 1, v[148:149]
	v_or_b32_e32 v128, 0x100, v128
	v_lshl_add_u64 v[148:149], s[78:79], 0, v[128:129]
	v_mov_b32_e32 v134, v144
	v_mov_b32_e32 v135, v144
	v_mov_b32_e32 v145, v144
	v_pk_mul_f32 v[150:151], v[90:91], v[134:135]
	v_pk_mul_f32 v[160:161], v[88:89], v[144:145]
	v_pk_mul_f32 v[134:135], v[82:83], v[134:135]
	v_pk_mul_f32 v[144:145], v[80:81], v[144:145]
	s_mov_b64 s[68:69], -1
	s_and_b64 vcc, exec, s[12:13]
	s_nop 1
	v_mov_b32_e32 v130, v236
	v_mov_b32_e32 v131, v237
	v_mov_b32_e32 v132, v238
	v_mov_b32_e32 v133, v239
	v_lshlrev_b32_e32 v128, 16, v130
	v_and_b32_e32 v129, 0xffff0000, v130
	v_lshlrev_b32_e32 v130, 16, v131
	v_and_b32_e32 v131, 0xffff0000, v131
	v_pk_fma_f32 v[130:131], v[138:139], v[150:151], v[130:131]
	v_lshlrev_b32_e32 v150, 16, v132
	v_and_b32_e32 v151, 0xffff0000, v132
	v_lshlrev_b32_e32 v132, 16, v133
	v_and_b32_e32 v133, 0xffff0000, v133
	v_pk_fma_f32 v[128:129], v[142:143], v[160:161], v[128:129]
	v_pk_fma_f32 v[134:135], v[136:137], v[134:135], v[132:133]
	v_pk_fma_f32 v[132:133], v[140:141], v[144:145], v[150:151]
	s_cbranch_vccnz .LBB0_114
	s_mov_b64 s[68:69], 0
	global_store_dwordx4 v[146:147], v[128:131], off offset:512
	global_store_dwordx4 v[146:147], v[132:135], off offset:528

; __device__ __forceinline__ unsigned cvt_pk_bf16(float lo, float hi) { const f32x2 v = (f32x2){lo, hi}; return __builtin_bit_cast(unsigned, __builtin_convertvector(v, bf16v2)); }
; __device__ __forceinline__ f32x4 bfx4_lo(u32x4 w) { return (f32x4){bf_lo(w.x), bf_hi(w.x), bf_lo(w.y), bf_hi(w.y)}; }
; __device__ __forceinline__ f32x4 bfx4_hi(u32x4 w) { return (f32x4){bf_lo(w.z), bf_hi(w.z), bf_lo(w.w), bf_hi(w.w)}; }
; __device__ __forceinline__ void fused_epi(f32x4 (&acc)[2][2][4][2], const Unit& u, int wr, int wc, int fr, int fq, LAS unsigned char* xl, int wid, int lane, const FuseArgs& f) {
;     ...
;             for (int m = 0; m < 4; ++m) { const int r = ai * HALF + wr * 64 + m * 16 + fr; const float rstd = S[r];
; #pragma unroll
;                 for (int bj = 0; bj < 2; ++bj) { const size_t off = (size_t)(pm * BM + r) * DM + colb + bj * HALF;
;                     const u32x4 xw = *(const u32x4*)((const bf16_t*)(f.ws + WS_XR) + off);
;                     const f32x4 x0 = bfx4_lo(xw) + Gv[bj][0] * (acc[ai][bj][m][0] * rstd), x1 = bfx4_hi(xw) + Gv[bj][1] * (acc[ai][bj][m][1] * rstd);
;                     if (f.out_f32) { *(f32x4*)(f.xoutf + off) = x0; *(f32x4*)(f.xoutf + off + 4) = x1; acc[ai][bj][m][0] = x0; acc[ai][bj][m][1] = x1; }
;                     else { u32x4 w; w.x = cvt_pk_bf16(x0[0], x0[1]); w.y = cvt_pk_bf16(x0[2], x0[3]); w.z = cvt_pk_bf16(x1[0], x1[1]); w.w = cvt_pk_bf16(x1[2], x1[3]);
;                         *(u32x4*)((bf16_t*)(f.ws + WS_XR) + off) = w; acc[ai][bj][m][0] = bfx4_lo(w); acc[ai][bj][m][1] = bfx4_hi(w); } }
.LBB0_116:
	v_lshlrev_b32_e32 v217, 11, v206
	v_lshl_add_u32 v217, v213, 1, v217
	global_load_dwordx4 v[112:115], v217, s[34:35] offset:256
	v_lshlrev_b32_e32 v217, 11, v208
	v_lshl_add_u32 v217, v213, 1, v217
	global_load_dwordx4 v[116:119], v217, s[34:35]
	global_load_dwordx4 v[88:91], v217, s[34:35] offset:256
	v_lshlrev_b32_e32 v217, 11, v210
	v_lshl_add_u32 v217, v213, 1, v217
	global_load_dwordx4 v[80:83], v217, s[34:35]
	s_nop 1
	v_add_u32_e32 v128, s9, v200
	v_ashrrev_i32_e32 v129, 31, v128
	v_lshlrev_b64 v[128:129], 10, v[128:129]
	v_lshl_add_u64 v[148:149], v[128:129], 0, v[176:177]
	v_lshl_add_u64 v[150:151], v[148:149], 1, s[78:79]
	ds_read_b32 v144, v201
	s_mov_b64 s[68:69], -1
	s_and_b64 vcc, exec, s[12:13]
	s_waitcnt lgkmcnt(0)
	v_pk_mul_f32 v[134:135], v[110:111], v[144:145] op_sel_hi:[1,0]
	v_pk_mul_f32 v[146:147], v[108:109], v[144:145] op_sel_hi:[1,0]
	v_pk_mul_f32 v[160:161], v[100:101], v[144:145] op_sel_hi:[1,0]
	s_nop 1
	v_mov_b32_e32 v130, v240
	v_mov_b32_e32 v131, v241
	v_mov_b32_e32 v132, v242
	v_mov_b32_e32 v133, v243
	v_lshlrev_b32_e32 v128, 16, v130
	v_and_b32_e32 v129, 0xffff0000, v130
	v_lshlrev_b32_e32 v130, 16, v131
	v_and_b32_e32 v131, 0xffff0000, v131
	v_pk_fma_f32 v[130:131], v[182:183], v[134:135], v[130:131]
	v_pk_fma_f32 v[128:129], v[184:185], v[146:147], v[128:129]
	v_lshlrev_b32_e32 v146, 16, v132
	v_and_b32_e32 v147, 0xffff0000, v132
	v_lshlrev_b32_e32 v132, 16, v133
	v_and_b32_e32 v133, 0xffff0000, v133
	v_pk_mul_f32 v[134:135], v[102:103], v[144:145] op_sel_hi:[1,0]
	s_nop 0
	v_pk_fma_f32 v[134:135], v[178:179], v[134:135], v[132:133]
	v_pk_fma_f32 v[132:133], v[180:181], v[160:161], v[146:147]
	v_lshl_add_u64 v[146:147], v[148:149], 2, s[42:43]
	s_cbranch_vccnz .LBB0_118
	s_mov_b64 s[68:69], 0
	global_store_dwordx4 v[146:147], v[128:131], off
	global_store_dwordx4 v[146:147], v[132:135], off offset:16

; __device__ __forceinline__ unsigned cvt_pk_bf16(float lo, float hi) { const f32x2 v = (f32x2){lo, hi}; return __builtin_bit_cast(unsigned, __builtin_convertvector(v, bf16v2)); }
; __device__ __forceinline__ f32x4 bfx4_lo(u32x4 w) { return (f32x4){bf_lo(w.x), bf_hi(w.x), bf_lo(w.y), bf_hi(w.y)}; }
; __device__ __forceinline__ f32x4 bfx4_hi(u32x4 w) { return (f32x4){bf_lo(w.z), bf_hi(w.z), bf_lo(w.w), bf_hi(w.w)}; }
; __device__ __forceinline__ void fused_epi(f32x4 (&acc)[2][2][4][2], const Unit& u, int wr, int wc, int fr, int fq, LAS unsigned char* xl, int wid, int lane, const FuseArgs& f) {
;     ...
;             for (int m = 0; m < 4; ++m) { const int r = ai * HALF + wr * 64 + m * 16 + fr; const float rstd = S[r];
; #pragma unroll
;                 for (int bj = 0; bj < 2; ++bj) { const size_t off = (size_t)(pm * BM + r) * DM + colb + bj * HALF;
;                     const u32x4 xw = *(const u32x4*)((const bf16_t*)(f.ws + WS_XR) + off);
;                     const f32x4 x0 = bfx4_lo(xw) + Gv[bj][0] * (acc[ai][bj][m][0] * rstd), x1 = bfx4_hi(xw) + Gv[bj][1] * (acc[ai][bj][m][1] * rstd);
;                     if (f.out_f32) { *(f32x4*)(f.xoutf + off) = x0; *(f32x4*)(f.xoutf + off + 4) = x1; acc[ai][bj][m][0] = x0; acc[ai][bj][m][1] = x1; }
;                     else { u32x4 w; w.x = cvt_pk_bf16(x0[0], x0[1]); w.y = cvt_pk_bf16(x0[2], x0[3]); w.z = cvt_pk_bf16(x1[0], x1[1]); w.w = cvt_pk_bf16(x1[2], x1[3]);
;                         *(u32x4*)((bf16_t*)(f.ws + WS_XR) + off) = w; acc[ai][bj][m][0] = bfx4_lo(w); acc[ai][bj][m][1] = bfx4_hi(w); } }
.LBB0_120:
	s_nop 1
	v_lshlrev_b64 v[128:129], 1, v[148:149]
	v_or_b32_e32 v128, 0x100, v128
	v_lshl_add_u64 v[148:149], s[78:79], 0, v[128:129]
	v_mov_b32_e32 v134, v144
	v_mov_b32_e32 v135, v144
	v_mov_b32_e32 v145, v144
	v_pk_mul_f32 v[150:151], v[78:79], v[134:135]
	v_pk_mul_f32 v[160:161], v[76:77], v[144:145]
	v_pk_mul_f32 v[134:135], v[74:75], v[134:135]
	v_pk_mul_f32 v[144:145], v[72:73], v[144:145]
	s_mov_b64 s[68:69], -1
	s_and_b64 vcc, exec, s[12:13]
	s_nop 1
	v_mov_b32_e32 v130, v244
	v_mov_b32_e32 v131, v245
	v_mov_b32_e32 v132, v246
	v_mov_b32_e32 v133, v247
	v_lshlrev_b32_e32 v128, 16, v130
	v_and_b32_e32 v129, 0xffff0000, v130
	v_lshlrev_b32_e32 v130, 16, v131
	v_and_b32_e32 v131, 0xffff0000, v131
	v_pk_fma_f32 v[130:131], v[138:139], v[150:151], v[130:131]
	v_lshlrev_b32_e32 v150, 16, v132
	v_and_b32_e32 v151, 0xffff0000, v132
	v_lshlrev_b32_e32 v132, 16, v133
	v_and_b32_e32 v133, 0xffff0000, v133
	v_pk_fma_f32 v[128:129], v[142:143], v[160:161], v[128:129]
	v_pk_fma_f32 v[134:135], v[136:137], v[134:135], v[132:133]
	v_pk_fma_f32 v[132:133], v[140:141], v[144:145], v[150:151]
	s_cbranch_vccnz .LBB0_122
	s_mov_b64 s[68:69], 0
	global_store_dwordx4 v[146:147], v[128:131], off offset:512
	global_store_dwordx4 v[146:147], v[132:135], off offset:528

; __device__ __forceinline__ unsigned cvt_pk_bf16(float lo, float hi) { const f32x2 v = (f32x2){lo, hi}; return __builtin_bit_cast(unsigned, __builtin_convertvector(v, bf16v2)); }
; __device__ __forceinline__ f32x4 bfx4_lo(u32x4 w) { return (f32x4){bf_lo(w.x), bf_hi(w.x), bf_lo(w.y), bf_hi(w.y)}; }
; __device__ __forceinline__ f32x4 bfx4_hi(u32x4 w) { return (f32x4){bf_lo(w.z), bf_hi(w.z), bf_lo(w.w), bf_hi(w.w)}; }
; __device__ __forceinline__ void fused_epi(f32x4 (&acc)[2][2][4][2], const Unit& u, int wr, int wc, int fr, int fq, LAS unsigned char* xl, int wid, int lane, const FuseArgs& f) {
;     ...
;             for (int m = 0; m < 4; ++m) { const int r = ai * HALF + wr * 64 + m * 16 + fr; const float rstd = S[r];
; #pragma unroll
;                 for (int bj = 0; bj < 2; ++bj) { const size_t off = (size_t)(pm * BM + r) * DM + colb + bj * HALF;
;                     const u32x4 xw = *(const u32x4*)((const bf16_t*)(f.ws + WS_XR) + off);
;                     const f32x4 x0 = bfx4_lo(xw) + Gv[bj][0] * (acc[ai][bj][m][0] * rstd), x1 = bfx4_hi(xw) + Gv[bj][1] * (acc[ai][bj][m][1] * rstd);
;                     if (f.out_f32) { *(f32x4*)(f.xoutf + off) = x0; *(f32x4*)(f.xoutf + off + 4) = x1; acc[ai][bj][m][0] = x0; acc[ai][bj][m][1] = x1; }
;                     else { u32x4 w; w.x = cvt_pk_bf16(x0[0], x0[1]); w.y = cvt_pk_bf16(x0[2], x0[3]); w.z = cvt_pk_bf16(x1[0], x1[1]); w.w = cvt_pk_bf16(x1[2], x1[3]);
;                         *(u32x4*)((bf16_t*)(f.ws + WS_XR) + off) = w; acc[ai][bj][m][0] = bfx4_lo(w); acc[ai][bj][m][1] = bfx4_hi(w); } }
.LBB0_124:
	v_lshlrev_b32_e32 v217, 11, v210
	v_lshl_add_u32 v217, v213, 1, v217
	global_load_dwordx4 v[108:111], v217, s[34:35] offset:256
	s_nop 1
	v_add_u32_e32 v128, s9, v202
	v_ashrrev_i32_e32 v129, 31, v128
	v_lshlrev_b64 v[128:129], 10, v[128:129]
	v_lshl_add_u64 v[148:149], v[128:129], 0, v[176:177]
	v_lshl_add_u64 v[150:151], v[148:149], 1, s[78:79]
	ds_read_b32 v144, v203
	s_mov_b64 s[68:69], -1
	s_and_b64 vcc, exec, s[12:13]
	s_waitcnt lgkmcnt(0)
	v_pk_mul_f32 v[134:135], v[94:95], v[144:145] op_sel_hi:[1,0]
	v_pk_mul_f32 v[146:147], v[92:93], v[144:145] op_sel_hi:[1,0]
	v_pk_mul_f32 v[160:161], v[84:85], v[144:145] op_sel_hi:[1,0]
	s_nop 1
	v_mov_b32_e32 v130, v248
	v_mov_b32_e32 v131, v249
	v_mov_b32_e32 v132, v250
	v_mov_b32_e32 v133, v251
	v_lshlrev_b32_e32 v128, 16, v130
	v_and_b32_e32 v129, 0xffff0000, v130
	v_lshlrev_b32_e32 v130, 16, v131
	v_and_b32_e32 v131, 0xffff0000, v131
	v_pk_fma_f32 v[130:131], v[182:183], v[134:135], v[130:131]
	v_pk_fma_f32 v[128:129], v[184:185], v[146:147], v[128:129]
	v_lshlrev_b32_e32 v146, 16, v132
	v_and_b32_e32 v147, 0xffff0000, v132
	v_lshlrev_b32_e32 v132, 16, v133
	v_and_b32_e32 v133, 0xffff0000, v133
	v_pk_mul_f32 v[134:135], v[86:87], v[144:145] op_sel_hi:[1,0]
	s_nop 0
	v_pk_fma_f32 v[134:135], v[178:179], v[134:135], v[132:133]
	v_pk_fma_f32 v[132:133], v[180:181], v[160:161], v[146:147]
	v_lshl_add_u64 v[146:147], v[148:149], 2, s[42:43]
	s_cbranch_vccnz .LBB0_126
	s_mov_b64 s[68:69], 0
	global_store_dwordx4 v[146:147], v[128:131], off
	global_store_dwordx4 v[146:147], v[132:135], off offset:16

; __device__ __forceinline__ unsigned cvt_pk_bf16(float lo, float hi) { const f32x2 v = (f32x2){lo, hi}; return __builtin_bit_cast(unsigned, __builtin_convertvector(v, bf16v2)); }
; __device__ __forceinline__ f32x4 bfx4_lo(u32x4 w) { return (f32x4){bf_lo(w.x), bf_hi(w.x), bf_lo(w.y), bf_hi(w.y)}; }
; __device__ __forceinline__ f32x4 bfx4_hi(u32x4 w) { return (f32x4){bf_lo(w.z), bf_hi(w.z), bf_lo(w.w), bf_hi(w.w)}; }
; __device__ __forceinline__ void fused_epi(f32x4 (&acc)[2][2][4][2], const Unit& u, int wr, int wc, int fr, int fq, LAS unsigned char* xl, int wid, int lane, const FuseArgs& f) {
;     ...
;             for (int m = 0; m < 4; ++m) { const int r = ai * HALF + wr * 64 + m * 16 + fr; const float rstd = S[r];
; #pragma unroll
;                 for (int bj = 0; bj < 2; ++bj) { const size_t off = (size_t)(pm * BM + r) * DM + colb + bj * HALF;
;                     const u32x4 xw = *(const u32x4*)((const bf16_t*)(f.ws + WS_XR) + off);
;                     const f32x4 x0 = bfx4_lo(xw) + Gv[bj][0] * (acc[ai][bj][m][0] * rstd), x1 = bfx4_hi(xw) + Gv[bj][1] * (acc[ai][bj][m][1] * rstd);
;                     if (f.out_f32) { *(f32x4*)(f.xoutf + off) = x0; *(f32x4*)(f.xoutf + off + 4) = x1; acc[ai][bj][m][0] = x0; acc[ai][bj][m][1] = x1; }
;                     else { u32x4 w; w.x = cvt_pk_bf16(x0[0], x0[1]); w.y = cvt_pk_bf16(x0[2], x0[3]); w.z = cvt_pk_bf16(x1[0], x1[1]); w.w = cvt_pk_bf16(x1[2], x1[3]);
;                         *(u32x4*)((bf16_t*)(f.ws + WS_XR) + off) = w; acc[ai][bj][m][0] = bfx4_lo(w); acc[ai][bj][m][1] = bfx4_hi(w); } }
.LBB0_128:
	s_nop 1
	v_lshlrev_b64 v[128:129], 1, v[148:149]
	v_or_b32_e32 v128, 0x100, v128
	v_lshl_add_u64 v[148:149], s[78:79], 0, v[128:129]
	v_mov_b32_e32 v134, v144
	v_mov_b32_e32 v135, v144
	v_mov_b32_e32 v145, v144
	v_pk_mul_f32 v[150:151], v[70:71], v[134:135]
	v_pk_mul_f32 v[160:161], v[68:69], v[144:145]
	v_pk_mul_f32 v[134:135], v[66:67], v[134:135]
	v_pk_mul_f32 v[144:145], v[64:65], v[144:145]
	s_mov_b64 s[68:69], -1
	s_and_b64 vcc, exec, s[12:13]
	s_waitcnt vmcnt(13)
	s_nop 1
	v_mov_b32_e32 v130, v120
	v_mov_b32_e32 v131, v121
	v_mov_b32_e32 v132, v122
	v_mov_b32_e32 v133, v123
	v_lshlrev_b32_e32 v128, 16, v130
	v_and_b32_e32 v129, 0xffff0000, v130
	v_lshlrev_b32_e32 v130, 16, v131
	v_and_b32_e32 v131, 0xffff0000, v131
	v_pk_fma_f32 v[130:131], v[138:139], v[150:151], v[130:131]
	v_lshlrev_b32_e32 v150, 16, v132
	v_and_b32_e32 v151, 0xffff0000, v132
	v_lshlrev_b32_e32 v132, 16, v133
	v_and_b32_e32 v133, 0xffff0000, v133
	v_pk_fma_f32 v[128:129], v[142:143], v[160:161], v[128:129]
	v_pk_fma_f32 v[134:135], v[136:137], v[134:135], v[132:133]
	v_pk_fma_f32 v[132:133], v[140:141], v[144:145], v[150:151]
	s_cbranch_vccnz .LBB0_130
	s_mov_b64 s[68:69], 0
	global_store_dwordx4 v[146:147], v[128:131], off offset:512
	global_store_dwordx4 v[146:147], v[132:135], off offset:528

; __device__ __forceinline__ unsigned cvt_pk_bf16(float lo, float hi) { const f32x2 v = (f32x2){lo, hi}; return __builtin_bit_cast(unsigned, __builtin_convertvector(v, bf16v2)); }
; __device__ __forceinline__ f32x4 bfx4_lo(u32x4 w) { return (f32x4){bf_lo(w.x), bf_hi(w.x), bf_lo(w.y), bf_hi(w.y)}; }
; __device__ __forceinline__ f32x4 bfx4_hi(u32x4 w) { return (f32x4){bf_lo(w.z), bf_hi(w.z), bf_lo(w.w), bf_hi(w.w)}; }
; __device__ __forceinline__ void fused_epi(f32x4 (&acc)[2][2][4][2], const Unit& u, int wr, int wc, int fr, int fq, LAS unsigned char* xl, int wid, int lane, const FuseArgs& f) {
;     ...
;             for (int m = 0; m < 4; ++m) { const int r = ai * HALF + wr * 64 + m * 16 + fr; const float rstd = S[r];
; #pragma unroll
;                 for (int bj = 0; bj < 2; ++bj) { const size_t off = (size_t)(pm * BM + r) * DM + colb + bj * HALF;
;                     const u32x4 xw = *(const u32x4*)((const bf16_t*)(f.ws + WS_XR) + off);
;                     const f32x4 x0 = bfx4_lo(xw) + Gv[bj][0] * (acc[ai][bj][m][0] * rstd), x1 = bfx4_hi(xw) + Gv[bj][1] * (acc[ai][bj][m][1] * rstd);
;                     if (f.out_f32) { *(f32x4*)(f.xoutf + off) = x0; *(f32x4*)(f.xoutf + off + 4) = x1; acc[ai][bj][m][0] = x0; acc[ai][bj][m][1] = x1; }
;                     else { u32x4 w; w.x = cvt_pk_bf16(x0[0], x0[1]); w.y = cvt_pk_bf16(x0[2], x0[3]); w.z = cvt_pk_bf16(x1[0], x1[1]); w.w = cvt_pk_bf16(x1[2], x1[3]);
;                         *(u32x4*)((bf16_t*)(f.ws + WS_XR) + off) = w; acc[ai][bj][m][0] = bfx4_lo(w); acc[ai][bj][m][1] = bfx4_hi(w); } }
.LBB0_132:
	s_nop 1
	v_add_u32_e32 v128, s9, v204
	v_ashrrev_i32_e32 v129, 31, v128
	v_lshlrev_b64 v[128:129], 10, v[128:129]
	v_lshl_add_u64 v[148:149], v[128:129], 0, v[176:177]
	v_lshl_add_u64 v[150:151], v[148:149], 1, s[78:79]
	ds_read_b32 v144, v205
	s_mov_b64 s[68:69], -1
	s_and_b64 vcc, exec, s[12:13]
	s_waitcnt lgkmcnt(0)
	v_pk_mul_f32 v[134:135], v[62:63], v[144:145] op_sel_hi:[1,0]
	v_pk_mul_f32 v[146:147], v[60:61], v[144:145] op_sel_hi:[1,0]
	v_pk_mul_f32 v[160:161], v[56:57], v[144:145] op_sel_hi:[1,0]
	s_waitcnt vmcnt(13)
	s_nop 1
	v_mov_b32_e32 v130, v124
	v_mov_b32_e32 v131, v125
	v_mov_b32_e32 v132, v126
	v_mov_b32_e32 v133, v127
	v_lshlrev_b32_e32 v128, 16, v130
	v_and_b32_e32 v129, 0xffff0000, v130
	v_lshlrev_b32_e32 v130, 16, v131
	v_and_b32_e32 v131, 0xffff0000, v131
	v_pk_fma_f32 v[130:131], v[182:183], v[134:135], v[130:131]
	v_pk_fma_f32 v[128:129], v[184:185], v[146:147], v[128:129]
	v_lshlrev_b32_e32 v146, 16, v132
	v_and_b32_e32 v147, 0xffff0000, v132
	v_lshlrev_b32_e32 v132, 16, v133
	v_and_b32_e32 v133, 0xffff0000, v133
	v_pk_mul_f32 v[134:135], v[58:59], v[144:145] op_sel_hi:[1,0]
	s_nop 0
	v_pk_fma_f32 v[134:135], v[178:179], v[134:135], v[132:133]
	v_pk_fma_f32 v[132:133], v[180:181], v[160:161], v[146:147]
	v_lshl_add_u64 v[146:147], v[148:149], 2, s[42:43]
	s_cbranch_vccnz .LBB0_134
	s_mov_b64 s[68:69], 0
	global_store_dwordx4 v[146:147], v[128:131], off
	global_store_dwordx4 v[146:147], v[132:135], off offset:16

; __device__ __forceinline__ unsigned cvt_pk_bf16(float lo, float hi) { const f32x2 v = (f32x2){lo, hi}; return __builtin_bit_cast(unsigned, __builtin_convertvector(v, bf16v2)); }
; __device__ __forceinline__ f32x4 bfx4_lo(u32x4 w) { return (f32x4){bf_lo(w.x), bf_hi(w.x), bf_lo(w.y), bf_hi(w.y)}; }
; __device__ __forceinline__ f32x4 bfx4_hi(u32x4 w) { return (f32x4){bf_lo(w.z), bf_hi(w.z), bf_lo(w.w), bf_hi(w.w)}; }
; __device__ __forceinline__ void fused_epi(f32x4 (&acc)[2][2][4][2], const Unit& u, int wr, int wc, int fr, int fq, LAS unsigned char* xl, int wid, int lane, const FuseArgs& f) {
;     ...
;             for (int m = 0; m < 4; ++m) { const int r = ai * HALF + wr * 64 + m * 16 + fr; const float rstd = S[r];
; #pragma unroll
;                 for (int bj = 0; bj < 2; ++bj) { const size_t off = (size_t)(pm * BM + r) * DM + colb + bj * HALF;
;                     const u32x4 xw = *(const u32x4*)((const bf16_t*)(f.ws + WS_XR) + off);
;                     const f32x4 x0 = bfx4_lo(xw) + Gv[bj][0] * (acc[ai][bj][m][0] * rstd), x1 = bfx4_hi(xw) + Gv[bj][1] * (acc[ai][bj][m][1] * rstd);
;                     if (f.out_f32) { *(f32x4*)(f.xoutf + off) = x0; *(f32x4*)(f.xoutf + off + 4) = x1; acc[ai][bj][m][0] = x0; acc[ai][bj][m][1] = x1; }
;                     else { u32x4 w; w.x = cvt_pk_bf16(x0[0], x0[1]); w.y = cvt_pk_bf16(x0[2], x0[3]); w.z = cvt_pk_bf16(x1[0], x1[1]); w.w = cvt_pk_bf16(x1[2], x1[3]);
;                         *(u32x4*)((bf16_t*)(f.ws + WS_XR) + off) = w; acc[ai][bj][m][0] = bfx4_lo(w); acc[ai][bj][m][1] = bfx4_hi(w); } }
.LBB0_136:
	s_nop 1
	v_lshlrev_b64 v[128:129], 1, v[148:149]
	v_or_b32_e32 v128, 0x100, v128
	v_lshl_add_u64 v[148:149], s[78:79], 0, v[128:129]
	v_mov_b32_e32 v134, v144
	v_mov_b32_e32 v135, v144
	v_mov_b32_e32 v145, v144
	v_pk_mul_f32 v[150:151], v[46:47], v[134:135]
	v_pk_mul_f32 v[160:161], v[44:45], v[144:145]
	v_pk_mul_f32 v[134:135], v[38:39], v[134:135]
	v_pk_mul_f32 v[144:145], v[36:37], v[144:145]
	s_mov_b64 s[68:69], -1
	s_and_b64 vcc, exec, s[12:13]
	s_waitcnt vmcnt(13)
	s_nop 1
	v_mov_b32_e32 v130, v96
	v_mov_b32_e32 v131, v97
	v_mov_b32_e32 v132, v98
	v_mov_b32_e32 v133, v99
	v_lshlrev_b32_e32 v128, 16, v130
	v_and_b32_e32 v129, 0xffff0000, v130
	v_lshlrev_b32_e32 v130, 16, v131
	v_and_b32_e32 v131, 0xffff0000, v131
	v_pk_fma_f32 v[130:131], v[138:139], v[150:151], v[130:131]
	v_lshlrev_b32_e32 v150, 16, v132
	v_and_b32_e32 v151, 0xffff0000, v132
	v_lshlrev_b32_e32 v132, 16, v133
	v_and_b32_e32 v133, 0xffff0000, v133
	v_pk_fma_f32 v[128:129], v[142:143], v[160:161], v[128:129]
	v_pk_fma_f32 v[134:135], v[136:137], v[134:135], v[132:133]
	v_pk_fma_f32 v[132:133], v[140:141], v[144:145], v[150:151]
	s_cbranch_vccnz .LBB0_138
	s_mov_b64 s[68:69], 0
	global_store_dwordx4 v[146:147], v[128:131], off offset:512
	global_store_dwordx4 v[146:147], v[132:135], off offset:528

; __device__ __forceinline__ unsigned cvt_pk_bf16(float lo, float hi) { const f32x2 v = (f32x2){lo, hi}; return __builtin_bit_cast(unsigned, __builtin_convertvector(v, bf16v2)); }
; __device__ __forceinline__ f32x4 bfx4_lo(u32x4 w) { return (f32x4){bf_lo(w.x), bf_hi(w.x), bf_lo(w.y), bf_hi(w.y)}; }
; __device__ __forceinline__ f32x4 bfx4_hi(u32x4 w) { return (f32x4){bf_lo(w.z), bf_hi(w.z), bf_lo(w.w), bf_hi(w.w)}; }
; __device__ __forceinline__ void fused_epi(f32x4 (&acc)[2][2][4][2], const Unit& u, int wr, int wc, int fr, int fq, LAS unsigned char* xl, int wid, int lane, const FuseArgs& f) {
;     ...
;             for (int m = 0; m < 4; ++m) { const int r = ai * HALF + wr * 64 + m * 16 + fr; const float rstd = S[r];
; #pragma unroll
;                 for (int bj = 0; bj < 2; ++bj) { const size_t off = (size_t)(pm * BM + r) * DM + colb + bj * HALF;
;                     const u32x4 xw = *(const u32x4*)((const bf16_t*)(f.ws + WS_XR) + off);
;                     const f32x4 x0 = bfx4_lo(xw) + Gv[bj][0] * (acc[ai][bj][m][0] * rstd), x1 = bfx4_hi(xw) + Gv[bj][1] * (acc[ai][bj][m][1] * rstd);
;                     if (f.out_f32) { *(f32x4*)(f.xoutf + off) = x0; *(f32x4*)(f.xoutf + off + 4) = x1; acc[ai][bj][m][0] = x0; acc[ai][bj][m][1] = x1; }
;                     else { u32x4 w; w.x = cvt_pk_bf16(x0[0], x0[1]); w.y = cvt_pk_bf16(x0[2], x0[3]); w.z = cvt_pk_bf16(x1[0], x1[1]); w.w = cvt_pk_bf16(x1[2], x1[3]);
;                         *(u32x4*)((bf16_t*)(f.ws + WS_XR) + off) = w; acc[ai][bj][m][0] = bfx4_lo(w); acc[ai][bj][m][1] = bfx4_hi(w); } }
.LBB0_140:
	s_nop 1
	v_add_u32_e32 v128, s9, v206
	v_ashrrev_i32_e32 v129, 31, v128
	v_lshlrev_b64 v[128:129], 10, v[128:129]
	v_lshl_add_u64 v[148:149], v[128:129], 0, v[176:177]
	v_lshl_add_u64 v[150:151], v[148:149], 1, s[78:79]
	ds_read_b32 v144, v207
	s_mov_b64 s[68:69], -1
	s_and_b64 vcc, exec, s[12:13]
	s_waitcnt lgkmcnt(0)
	v_pk_mul_f32 v[134:135], v[54:55], v[144:145] op_sel_hi:[1,0]
	v_pk_mul_f32 v[146:147], v[52:53], v[144:145] op_sel_hi:[1,0]
	v_pk_mul_f32 v[160:161], v[48:49], v[144:145] op_sel_hi:[1,0]
	s_waitcnt vmcnt(13)
	s_nop 1
	v_mov_b32_e32 v130, v104
	v_mov_b32_e32 v131, v105
	v_mov_b32_e32 v132, v106
	v_mov_b32_e32 v133, v107
	v_lshlrev_b32_e32 v128, 16, v130
	v_and_b32_e32 v129, 0xffff0000, v130
	v_lshlrev_b32_e32 v130, 16, v131
	v_and_b32_e32 v131, 0xffff0000, v131
	v_pk_fma_f32 v[130:131], v[182:183], v[134:135], v[130:131]
	v_pk_fma_f32 v[128:129], v[184:185], v[146:147], v[128:129]
	v_lshlrev_b32_e32 v146, 16, v132
	v_and_b32_e32 v147, 0xffff0000, v132
	v_lshlrev_b32_e32 v132, 16, v133
	v_and_b32_e32 v133, 0xffff0000, v133
	v_pk_mul_f32 v[134:135], v[50:51], v[144:145] op_sel_hi:[1,0]
	s_nop 0
	v_pk_fma_f32 v[134:135], v[178:179], v[134:135], v[132:133]
	v_pk_fma_f32 v[132:133], v[180:181], v[160:161], v[146:147]
	v_lshl_add_u64 v[146:147], v[148:149], 2, s[42:43]
	s_cbranch_vccnz .LBB0_142
	s_mov_b64 s[68:69], 0
	global_store_dwordx4 v[146:147], v[128:131], off
	global_store_dwordx4 v[146:147], v[132:135], off offset:16

; __device__ __forceinline__ unsigned cvt_pk_bf16(float lo, float hi) { const f32x2 v = (f32x2){lo, hi}; return __builtin_bit_cast(unsigned, __builtin_convertvector(v, bf16v2)); }
; __device__ __forceinline__ f32x4 bfx4_lo(u32x4 w) { return (f32x4){bf_lo(w.x), bf_hi(w.x), bf_lo(w.y), bf_hi(w.y)}; }
; __device__ __forceinline__ f32x4 bfx4_hi(u32x4 w) { return (f32x4){bf_lo(w.z), bf_hi(w.z), bf_lo(w.w), bf_hi(w.w)}; }
; __device__ __forceinline__ void fused_epi(f32x4 (&acc)[2][2][4][2], const Unit& u, int wr, int wc, int fr, int fq, LAS unsigned char* xl, int wid, int lane, const FuseArgs& f) {
;     ...
;             for (int m = 0; m < 4; ++m) { const int r = ai * HALF + wr * 64 + m * 16 + fr; const float rstd = S[r];
; #pragma unroll
;                 for (int bj = 0; bj < 2; ++bj) { const size_t off = (size_t)(pm * BM + r) * DM + colb + bj * HALF;
;                     const u32x4 xw = *(const u32x4*)((const bf16_t*)(f.ws + WS_XR) + off);
;                     const f32x4 x0 = bfx4_lo(xw) + Gv[bj][0] * (acc[ai][bj][m][0] * rstd), x1 = bfx4_hi(xw) + Gv[bj][1] * (acc[ai][bj][m][1] * rstd);
;                     if (f.out_f32) { *(f32x4*)(f.xoutf + off) = x0; *(f32x4*)(f.xoutf + off + 4) = x1; acc[ai][bj][m][0] = x0; acc[ai][bj][m][1] = x1; }
;                     else { u32x4 w; w.x = cvt_pk_bf16(x0[0], x0[1]); w.y = cvt_pk_bf16(x0[2], x0[3]); w.z = cvt_pk_bf16(x1[0], x1[1]); w.w = cvt_pk_bf16(x1[2], x1[3]);
;                         *(u32x4*)((bf16_t*)(f.ws + WS_XR) + off) = w; acc[ai][bj][m][0] = bfx4_lo(w); acc[ai][bj][m][1] = bfx4_hi(w); } }
.LBB0_144:
	s_nop 1
	v_lshlrev_b64 v[128:129], 1, v[148:149]
	v_or_b32_e32 v128, 0x100, v128
	v_lshl_add_u64 v[148:149], s[78:79], 0, v[128:129]
	v_mov_b32_e32 v134, v144
	v_mov_b32_e32 v135, v144
	v_mov_b32_e32 v145, v144
	v_pk_mul_f32 v[150:151], v[30:31], v[134:135]
	v_pk_mul_f32 v[160:161], v[28:29], v[144:145]
	v_pk_mul_f32 v[134:135], v[22:23], v[134:135]
	v_pk_mul_f32 v[144:145], v[20:21], v[144:145]
	s_mov_b64 s[68:69], -1
	s_and_b64 vcc, exec, s[12:13]
	s_waitcnt vmcnt(11)
	s_nop 1
	v_mov_b32_e32 v130, v112
	v_mov_b32_e32 v131, v113
	v_mov_b32_e32 v132, v114
	v_mov_b32_e32 v133, v115
	v_lshlrev_b32_e32 v128, 16, v130
	v_and_b32_e32 v129, 0xffff0000, v130
	v_lshlrev_b32_e32 v130, 16, v131
	v_and_b32_e32 v131, 0xffff0000, v131
	v_pk_fma_f32 v[130:131], v[138:139], v[150:151], v[130:131]
	v_lshlrev_b32_e32 v150, 16, v132
	v_and_b32_e32 v151, 0xffff0000, v132
	v_lshlrev_b32_e32 v132, 16, v133
	v_and_b32_e32 v133, 0xffff0000, v133
	v_pk_fma_f32 v[128:129], v[142:143], v[160:161], v[128:129]
	v_pk_fma_f32 v[134:135], v[136:137], v[134:135], v[132:133]
	v_pk_fma_f32 v[132:133], v[140:141], v[144:145], v[150:151]
	s_cbranch_vccnz .LBB0_146
	s_mov_b64 s[68:69], 0
	global_store_dwordx4 v[146:147], v[128:131], off offset:512
	global_store_dwordx4 v[146:147], v[132:135], off offset:528

; __device__ __forceinline__ unsigned cvt_pk_bf16(float lo, float hi) { const f32x2 v = (f32x2){lo, hi}; return __builtin_bit_cast(unsigned, __builtin_convertvector(v, bf16v2)); }
; __device__ __forceinline__ f32x4 bfx4_lo(u32x4 w) { return (f32x4){bf_lo(w.x), bf_hi(w.x), bf_lo(w.y), bf_hi(w.y)}; }
; __device__ __forceinline__ f32x4 bfx4_hi(u32x4 w) { return (f32x4){bf_lo(w.z), bf_hi(w.z), bf_lo(w.w), bf_hi(w.w)}; }
; __device__ __forceinline__ void fused_epi(f32x4 (&acc)[2][2][4][2], const Unit& u, int wr, int wc, int fr, int fq, LAS unsigned char* xl, int wid, int lane, const FuseArgs& f) {
;     ...
;             for (int m = 0; m < 4; ++m) { const int r = ai * HALF + wr * 64 + m * 16 + fr; const float rstd = S[r];
; #pragma unroll
;                 for (int bj = 0; bj < 2; ++bj) { const size_t off = (size_t)(pm * BM + r) * DM + colb + bj * HALF;
;                     const u32x4 xw = *(const u32x4*)((const bf16_t*)(f.ws + WS_XR) + off);
;                     const f32x4 x0 = bfx4_lo(xw) + Gv[bj][0] * (acc[ai][bj][m][0] * rstd), x1 = bfx4_hi(xw) + Gv[bj][1] * (acc[ai][bj][m][1] * rstd);
;                     if (f.out_f32) { *(f32x4*)(f.xoutf + off) = x0; *(f32x4*)(f.xoutf + off + 4) = x1; acc[ai][bj][m][0] = x0; acc[ai][bj][m][1] = x1; }
;                     else { u32x4 w; w.x = cvt_pk_bf16(x0[0], x0[1]); w.y = cvt_pk_bf16(x0[2], x0[3]); w.z = cvt_pk_bf16(x1[0], x1[1]); w.w = cvt_pk_bf16(x1[2], x1[3]);
;                         *(u32x4*)((bf16_t*)(f.ws + WS_XR) + off) = w; acc[ai][bj][m][0] = bfx4_lo(w); acc[ai][bj][m][1] = bfx4_hi(w); } }
.LBB0_148:
	s_nop 1
	v_add_u32_e32 v128, s9, v208
	v_ashrrev_i32_e32 v129, 31, v128
	v_lshlrev_b64 v[128:129], 10, v[128:129]
	v_lshl_add_u64 v[148:149], v[128:129], 0, v[176:177]
	v_lshl_add_u64 v[150:151], v[148:149], 1, s[78:79]
	ds_read_b32 v144, v209
	s_mov_b64 s[68:69], -1
	s_and_b64 vcc, exec, s[12:13]
	s_waitcnt lgkmcnt(0)
	v_pk_mul_f32 v[134:135], v[42:43], v[144:145] op_sel_hi:[1,0]
	v_pk_mul_f32 v[146:147], v[40:41], v[144:145] op_sel_hi:[1,0]
	v_pk_mul_f32 v[160:161], v[32:33], v[144:145] op_sel_hi:[1,0]
	s_waitcnt vmcnt(11)
	s_nop 1
	v_mov_b32_e32 v130, v116
	v_mov_b32_e32 v131, v117
	v_mov_b32_e32 v132, v118
	v_mov_b32_e32 v133, v119
	v_lshlrev_b32_e32 v128, 16, v130
	v_and_b32_e32 v129, 0xffff0000, v130
	v_lshlrev_b32_e32 v130, 16, v131
	v_and_b32_e32 v131, 0xffff0000, v131
	v_pk_fma_f32 v[130:131], v[182:183], v[134:135], v[130:131]
	v_pk_fma_f32 v[128:129], v[184:185], v[146:147], v[128:129]
	v_lshlrev_b32_e32 v146, 16, v132
	v_and_b32_e32 v147, 0xffff0000, v132
	v_lshlrev_b32_e32 v132, 16, v133
	v_and_b32_e32 v133, 0xffff0000, v133
	v_pk_mul_f32 v[134:135], v[34:35], v[144:145] op_sel_hi:[1,0]
	s_nop 0
	v_pk_fma_f32 v[134:135], v[178:179], v[134:135], v[132:133]
	v_pk_fma_f32 v[132:133], v[180:181], v[160:161], v[146:147]
	v_lshl_add_u64 v[146:147], v[148:149], 2, s[42:43]
	s_cbranch_vccnz .LBB0_150
	s_mov_b64 s[68:69], 0
	global_store_dwordx4 v[146:147], v[128:131], off
	global_store_dwordx4 v[146:147], v[132:135], off offset:16

; __device__ __forceinline__ unsigned cvt_pk_bf16(float lo, float hi) { const f32x2 v = (f32x2){lo, hi}; return __builtin_bit_cast(unsigned, __builtin_convertvector(v, bf16v2)); }
; __device__ __forceinline__ f32x4 bfx4_lo(u32x4 w) { return (f32x4){bf_lo(w.x), bf_hi(w.x), bf_lo(w.y), bf_hi(w.y)}; }
; __device__ __forceinline__ f32x4 bfx4_hi(u32x4 w) { return (f32x4){bf_lo(w.z), bf_hi(w.z), bf_lo(w.w), bf_hi(w.w)}; }
; __device__ __forceinline__ void fused_epi(f32x4 (&acc)[2][2][4][2], const Unit& u, int wr, int wc, int fr, int fq, LAS unsigned char* xl, int wid, int lane, const FuseArgs& f) {
;     ...
;             for (int m = 0; m < 4; ++m) { const int r = ai * HALF + wr * 64 + m * 16 + fr; const float rstd = S[r];
; #pragma unroll
;                 for (int bj = 0; bj < 2; ++bj) { const size_t off = (size_t)(pm * BM + r) * DM + colb + bj * HALF;
;                     const u32x4 xw = *(const u32x4*)((const bf16_t*)(f.ws + WS_XR) + off);
;                     const f32x4 x0 = bfx4_lo(xw) + Gv[bj][0] * (acc[ai][bj][m][0] * rstd), x1 = bfx4_hi(xw) + Gv[bj][1] * (acc[ai][bj][m][1] * rstd);
;                     if (f.out_f32) { *(f32x4*)(f.xoutf + off) = x0; *(f32x4*)(f.xoutf + off + 4) = x1; acc[ai][bj][m][0] = x0; acc[ai][bj][m][1] = x1; }
;                     else { u32x4 w; w.x = cvt_pk_bf16(x0[0], x0[1]); w.y = cvt_pk_bf16(x0[2], x0[3]); w.z = cvt_pk_bf16(x1[0], x1[1]); w.w = cvt_pk_bf16(x1[2], x1[3]);
;                         *(u32x4*)((bf16_t*)(f.ws + WS_XR) + off) = w; acc[ai][bj][m][0] = bfx4_lo(w); acc[ai][bj][m][1] = bfx4_hi(w); } }
.LBB0_152:
	s_nop 1
	v_lshlrev_b64 v[128:129], 1, v[148:149]
	v_or_b32_e32 v128, 0x100, v128
	v_lshl_add_u64 v[148:149], s[78:79], 0, v[128:129]
	v_mov_b32_e32 v134, v144
	v_mov_b32_e32 v135, v144
	v_mov_b32_e32 v145, v144
	v_pk_mul_f32 v[150:151], v[14:15], v[134:135]
	v_pk_mul_f32 v[160:161], v[12:13], v[144:145]
	v_pk_mul_f32 v[134:135], v[10:11], v[134:135]
	v_pk_mul_f32 v[144:145], v[8:9], v[144:145]
	s_mov_b64 s[68:69], -1
	s_and_b64 vcc, exec, s[12:13]
	s_waitcnt vmcnt(11)
	s_nop 1
	v_mov_b32_e32 v130, v88
	v_mov_b32_e32 v131, v89
	v_mov_b32_e32 v132, v90
	v_mov_b32_e32 v133, v91
	v_lshlrev_b32_e32 v128, 16, v130
	v_and_b32_e32 v129, 0xffff0000, v130
	v_lshlrev_b32_e32 v130, 16, v131
	v_and_b32_e32 v131, 0xffff0000, v131
	v_pk_fma_f32 v[130:131], v[138:139], v[150:151], v[130:131]
	v_lshlrev_b32_e32 v150, 16, v132
	v_and_b32_e32 v151, 0xffff0000, v132
	v_lshlrev_b32_e32 v132, 16, v133
	v_and_b32_e32 v133, 0xffff0000, v133
	v_pk_fma_f32 v[128:129], v[142:143], v[160:161], v[128:129]
	v_pk_fma_f32 v[134:135], v[136:137], v[134:135], v[132:133]
	v_pk_fma_f32 v[132:133], v[140:141], v[144:145], v[150:151]
	s_cbranch_vccnz .LBB0_154
	s_mov_b64 s[68:69], 0
	global_store_dwordx4 v[146:147], v[128:131], off offset:512
	global_store_dwordx4 v[146:147], v[132:135], off offset:528

; __device__ __forceinline__ unsigned cvt_pk_bf16(float lo, float hi) { const f32x2 v = (f32x2){lo, hi}; return __builtin_bit_cast(unsigned, __builtin_convertvector(v, bf16v2)); }
; __device__ __forceinline__ f32x4 bfx4_lo(u32x4 w) { return (f32x4){bf_lo(w.x), bf_hi(w.x), bf_lo(w.y), bf_hi(w.y)}; }
; __device__ __forceinline__ f32x4 bfx4_hi(u32x4 w) { return (f32x4){bf_lo(w.z), bf_hi(w.z), bf_lo(w.w), bf_hi(w.w)}; }
; __device__ __forceinline__ void fused_epi(f32x4 (&acc)[2][2][4][2], const Unit& u, int wr, int wc, int fr, int fq, LAS unsigned char* xl, int wid, int lane, const FuseArgs& f) {
;     ...
;             for (int m = 0; m < 4; ++m) { const int r = ai * HALF + wr * 64 + m * 16 + fr; const float rstd = S[r];
; #pragma unroll
;                 for (int bj = 0; bj < 2; ++bj) { const size_t off = (size_t)(pm * BM + r) * DM + colb + bj * HALF;
;                     const u32x4 xw = *(const u32x4*)((const bf16_t*)(f.ws + WS_XR) + off);
;                     const f32x4 x0 = bfx4_lo(xw) + Gv[bj][0] * (acc[ai][bj][m][0] * rstd), x1 = bfx4_hi(xw) + Gv[bj][1] * (acc[ai][bj][m][1] * rstd);
;                     if (f.out_f32) { *(f32x4*)(f.xoutf + off) = x0; *(f32x4*)(f.xoutf + off + 4) = x1; acc[ai][bj][m][0] = x0; acc[ai][bj][m][1] = x1; }
;                     else { u32x4 w; w.x = cvt_pk_bf16(x0[0], x0[1]); w.y = cvt_pk_bf16(x0[2], x0[3]); w.z = cvt_pk_bf16(x1[0], x1[1]); w.w = cvt_pk_bf16(x1[2], x1[3]);
;                         *(u32x4*)((bf16_t*)(f.ws + WS_XR) + off) = w; acc[ai][bj][m][0] = bfx4_lo(w); acc[ai][bj][m][1] = bfx4_hi(w); } }
.LBB0_156:
	s_nop 1
	v_add_u32_e32 v128, s9, v210
	v_ashrrev_i32_e32 v129, 31, v128
	v_lshlrev_b64 v[128:129], 10, v[128:129]
	v_lshl_add_u64 v[146:147], v[128:129], 0, v[176:177]
	v_lshl_add_u64 v[148:149], v[146:147], 1, s[78:79]
	ds_read_b32 v144, v211
	s_mov_b64 s[68:69], -1
	s_and_b64 vcc, exec, s[12:13]
	s_waitcnt lgkmcnt(0)
	v_pk_mul_f32 v[134:135], v[26:27], v[144:145] op_sel_hi:[1,0]
	v_pk_mul_f32 v[150:151], v[24:25], v[144:145] op_sel_hi:[1,0]
	v_pk_mul_f32 v[160:161], v[16:17], v[144:145] op_sel_hi:[1,0]
	s_waitcnt vmcnt(11)
	s_nop 1
	v_mov_b32_e32 v130, v80
	v_mov_b32_e32 v131, v81
	v_mov_b32_e32 v132, v82
	v_mov_b32_e32 v133, v83
	v_lshlrev_b32_e32 v128, 16, v130
	v_and_b32_e32 v129, 0xffff0000, v130
	v_lshlrev_b32_e32 v130, 16, v131
	v_and_b32_e32 v131, 0xffff0000, v131
	v_pk_fma_f32 v[130:131], v[182:183], v[134:135], v[130:131]
	v_pk_fma_f32 v[128:129], v[184:185], v[150:151], v[128:129]
	v_lshlrev_b32_e32 v150, 16, v132
	v_and_b32_e32 v151, 0xffff0000, v132
	v_lshlrev_b32_e32 v132, 16, v133
	v_and_b32_e32 v133, 0xffff0000, v133
	v_pk_mul_f32 v[134:135], v[18:19], v[144:145] op_sel_hi:[1,0]
	s_nop 0
	v_pk_fma_f32 v[134:135], v[178:179], v[134:135], v[132:133]
	v_pk_fma_f32 v[132:133], v[180:181], v[160:161], v[150:151]
	v_lshl_add_u64 v[150:151], v[146:147], 2, s[42:43]
	s_cbranch_vccnz .LBB0_158
	s_mov_b64 s[68:69], 0
	global_store_dwordx4 v[150:151], v[128:131], off
	global_store_dwordx4 v[150:151], v[132:135], off offset:16

; __device__ __forceinline__ unsigned cvt_pk_bf16(float lo, float hi) { const f32x2 v = (f32x2){lo, hi}; return __builtin_bit_cast(unsigned, __builtin_convertvector(v, bf16v2)); }
; __device__ __forceinline__ f32x4 bfx4_lo(u32x4 w) { return (f32x4){bf_lo(w.x), bf_hi(w.x), bf_lo(w.y), bf_hi(w.y)}; }
; __device__ __forceinline__ f32x4 bfx4_hi(u32x4 w) { return (f32x4){bf_lo(w.z), bf_hi(w.z), bf_lo(w.w), bf_hi(w.w)}; }
; __device__ __forceinline__ void fused_epi(f32x4 (&acc)[2][2][4][2], const Unit& u, int wr, int wc, int fr, int fq, LAS unsigned char* xl, int wid, int lane, const FuseArgs& f) {
;     ...
;             for (int m = 0; m < 4; ++m) { const int r = ai * HALF + wr * 64 + m * 16 + fr; const float rstd = S[r];
; #pragma unroll
;                 for (int bj = 0; bj < 2; ++bj) { const size_t off = (size_t)(pm * BM + r) * DM + colb + bj * HALF;
;                     const u32x4 xw = *(const u32x4*)((const bf16_t*)(f.ws + WS_XR) + off);
;                     const f32x4 x0 = bfx4_lo(xw) + Gv[bj][0] * (acc[ai][bj][m][0] * rstd), x1 = bfx4_hi(xw) + Gv[bj][1] * (acc[ai][bj][m][1] * rstd);
;                     if (f.out_f32) { *(f32x4*)(f.xoutf + off) = x0; *(f32x4*)(f.xoutf + off + 4) = x1; acc[ai][bj][m][0] = x0; acc[ai][bj][m][1] = x1; }
;                     else { u32x4 w; w.x = cvt_pk_bf16(x0[0], x0[1]); w.y = cvt_pk_bf16(x0[2], x0[3]); w.z = cvt_pk_bf16(x1[0], x1[1]); w.w = cvt_pk_bf16(x1[2], x1[3]);
;                         *(u32x4*)((bf16_t*)(f.ws + WS_XR) + off) = w; acc[ai][bj][m][0] = bfx4_lo(w); acc[ai][bj][m][1] = bfx4_hi(w); } }
.LBB0_160:
	s_nop 1
	v_lshlrev_b64 v[128:129], 1, v[146:147]
	v_or_b32_e32 v128, 0x100, v128
	v_lshl_add_u64 v[146:147], s[78:79], 0, v[128:129]
	v_mov_b32_e32 v145, v144
	v_mov_b32_e32 v132, v144
	v_mov_b32_e32 v133, v144
	v_pk_mul_f32 v[134:135], v[6:7], v[132:133]
	v_pk_mul_f32 v[148:149], v[4:5], v[144:145]
	v_pk_mul_f32 v[160:161], v[2:3], v[132:133]
	v_pk_mul_f32 v[144:145], v[0:1], v[144:145]
	s_and_b64 vcc, exec, s[12:13]
	s_mov_b64 s[12:13], -1
	s_waitcnt vmcnt(9)
	s_nop 1
	v_mov_b32_e32 v128, v108
	v_mov_b32_e32 v129, v109
	v_mov_b32_e32 v130, v110
	v_mov_b32_e32 v131, v111
	v_lshlrev_b32_e32 v132, 16, v128
	v_and_b32_e32 v133, 0xffff0000, v128
	v_lshlrev_b32_e32 v128, 16, v129
	v_and_b32_e32 v129, 0xffff0000, v129
	v_lshlrev_b32_e32 v176, 16, v130
	v_and_b32_e32 v177, 0xffff0000, v130
	v_lshlrev_b32_e32 v130, 16, v131
	v_and_b32_e32 v131, 0xffff0000, v131
	v_pk_fma_f32 v[134:135], v[138:139], v[134:135], v[128:129]
	v_pk_fma_f32 v[132:133], v[142:143], v[148:149], v[132:133]
	v_pk_fma_f32 v[130:131], v[136:137], v[160:161], v[130:131]
	v_pk_fma_f32 v[128:129], v[140:141], v[144:145], v[176:177]
	s_cbranch_vccnz .LBB0_162
	s_mov_b64 s[12:13], 0
	global_store_dwordx4 v[150:151], v[132:135], off offset:512
	global_store_dwordx4 v[150:151], v[128:131], off offset:528

; __device__ __forceinline__ void panel_rms(const f32x4 (&v)[2][2][4][2], int pm, int pn, int wr, int wc, int fr, int fq, LAS unsigned char* xl, int wid, int lane, float* slots, unsigned* cnt) {
;     ...
; #pragma unroll
;     for (int ai = 0; ai < 2; ++ai)
; #pragma unroll
;         for (int m = 0; m < 4; ++m) { float q = 0.f;
; #pragma unroll
;             for (int bj = 0; bj < 2; ++bj)
; #pragma unroll
;                 for (int n = 0; n < 2; ++n) { const f32x4 x = v[ai][bj][m][n]; q += (x[0] * x[0] + x[1] * x[1]) + (x[2] * x[2] + x[3] * x[3]); }
;             q += __shfl_xor(q, 16); q += __shfl_xor(q, 32);
;             if (fq == 0) P[(ai * HALF + wr * 64 + m * 16 + fr) * 4 + wc] = q; }
; __device__ __forceinline__ void fused_epi(f32x4 (&acc)[2][2][4][2], const Unit& u, int wr, int wc, int fr, int fq, LAS unsigned char* xl, int wid, int lane, const FuseArgs& f) {
;     ...
;                 for (int bj = 0; bj < 2; ++bj) { const size_t off = (size_t)(pm * BM + r) * DM + colb + bj * HALF;
;                     const u32x4 xw = *(const u32x4*)((const bf16_t*)(f.ws + WS_XR) + off);
.LBB0_250:
	s_lshl_b32 s32, s53, 19
	s_add_u32 s34, s78, s32
	s_addc_u32 s35, s79, 0
	s_lshl_b32 s32, s16, 9
	s_add_u32 s34, s34, s32
	s_addc_u32 s35, s35, 0
	v_lshlrev_b32_e32 v217, 11, v167
	v_lshl_add_u32 v217, v191, 1, v217
	global_load_dwordx4 v[224:227], v217, s[34:35]
	global_load_dwordx4 v[228:231], v217, s[34:35] offset:256
	v_lshlrev_b32_e32 v217, 11, v176
	v_lshl_add_u32 v217, v191, 1, v217
	global_load_dwordx4 v[232:235], v217, s[34:35]
	global_load_dwordx4 v[236:239], v217, s[34:35] offset:256
	v_lshlrev_b32_e32 v217, 11, v178
	v_lshl_add_u32 v217, v191, 1, v217
	global_load_dwordx4 v[240:243], v217, s[34:35]
	global_load_dwordx4 v[244:247], v217, s[34:35] offset:256
	v_lshlrev_b32_e32 v217, 11, v180
	v_lshl_add_u32 v217, v191, 1, v217
	global_load_dwordx4 v[248:251], v217, s[34:35]
	v_mul_f32_e32 v140, v125, v125
	v_mul_f32_e32 v141, v127, v127
	v_fmac_f32_e32 v140, v124, v124
	v_fmac_f32_e32 v141, v126, v126
	v_add_f32_e32 v140, v140, v141
	v_mul_f32_e32 v141, v121, v121
	v_mul_f32_e32 v142, v123, v123
	v_fmac_f32_e32 v141, v120, v120
	v_fmac_f32_e32 v142, v122, v122
	v_add_f32_e32 v141, v141, v142
	v_add_f32_e32 v140, v140, v141
	v_mul_f32_e32 v141, v105, v105
	v_mul_f32_e32 v142, v107, v107
	v_fmac_f32_e32 v141, v104, v104
	v_fmac_f32_e32 v142, v106, v106
	v_and_b32_e32 v139, 64, v221
	v_add_f32_e32 v141, v141, v142
	v_xor_b32_e32 v138, 16, v221
	v_add_u32_e32 v139, 64, v139
	v_add_f32_e32 v140, v140, v141
	v_mul_f32_e32 v141, v97, v97
	v_mul_f32_e32 v142, v99, v99
	v_cmp_lt_i32_e32 vcc, v138, v139
	v_fmac_f32_e32 v141, v96, v96
	v_fmac_f32_e32 v142, v98, v98
	v_cndmask_b32_e32 v138, v221, v138, vcc
	v_add_f32_e32 v141, v141, v142
	v_lshlrev_b32_e32 v138, 2, v138
	v_add_f32_e32 v140, v140, v141
	ds_bpermute_b32 v141, v138, v140
	v_xor_b32_e32 v142, 32, v221
	v_cmp_lt_i32_e32 vcc, v142, v139
	s_waitcnt lgkmcnt(0)
	v_add_f32_e32 v140, v140, v141
	v_cndmask_b32_e32 v139, v221, v142, vcc
	v_lshlrev_b32_e32 v139, 2, v139
	ds_bpermute_b32 v141, v139, v140
	s_and_saveexec_b64 s[68:69], s[4:5]
	s_cbranch_execz .LBB0_252
	s_waitcnt lgkmcnt(0)
	v_add_f32_e32 v140, v140, v141
	ds_write_b32 v194, v140

; __device__ __forceinline__ unsigned cvt_pk_bf16(float lo, float hi) { const f32x2 v = (f32x2){lo, hi}; return __builtin_bit_cast(unsigned, __builtin_convertvector(v, bf16v2)); }
; __device__ __forceinline__ f32x4 bfx4_lo(u32x4 w) { return (f32x4){bf_lo(w.x), bf_hi(w.x), bf_lo(w.y), bf_hi(w.y)}; }
; __device__ __forceinline__ f32x4 bfx4_hi(u32x4 w) { return (f32x4){bf_lo(w.z), bf_hi(w.z), bf_lo(w.w), bf_hi(w.w)}; }
; __device__ __forceinline__ void fused_epi(f32x4 (&acc)[2][2][4][2], const Unit& u, int wr, int wc, int fr, int fq, LAS unsigned char* xl, int wid, int lane, const FuseArgs& f) {
;     ...
;         for (int bj = 0; bj < 2; ++bj)
; #pragma unroll
;             for (int n = 0; n < 2; ++n) { const int c = colb + bj * HALF + 4 * n; Gv[bj][n] = *(const f32x4*)(f.modl + f.gate_off + mrow + c) * *(const f32x4*)(f.gpost + c); }
; #pragma unroll
;         for (int ai = 0; ai < 2; ++ai)
; #pragma unroll
;             for (int m = 0; m < 4; ++m) { const int r = ai * HALF + wr * 64 + m * 16 + fr; const float rstd = S[r];
; #pragma unroll
;                 for (int bj = 0; bj < 2; ++bj) { const size_t off = (size_t)(pm * BM + r) * DM + colb + bj * HALF;
;                     const u32x4 xw = *(const u32x4*)((const bf16_t*)(f.ws + WS_XR) + off);
;                     const f32x4 x0 = bfx4_lo(xw) + Gv[bj][0] * (acc[ai][bj][m][0] * rstd), x1 = bfx4_hi(xw) + Gv[bj][1] * (acc[ai][bj][m][1] * rstd);
;                     if (f.out_f32) { *(f32x4*)(f.xoutf + off) = x0; *(f32x4*)(f.xoutf + off + 4) = x1; acc[ai][bj][m][0] = x0; acc[ai][bj][m][1] = x1; }
;                     else { u32x4 w; w.x = cvt_pk_bf16(x0[0], x0[1]); w.y = cvt_pk_bf16(x0[2], x0[3]); w.z = cvt_pk_bf16(x1[0], x1[1]); w.w = cvt_pk_bf16(x1[2], x1[3]);
;                         *(u32x4*)((bf16_t*)(f.ws + WS_XR) + off) = w; acc[ai][bj][m][0] = bfx4_lo(w); acc[ai][bj][m][1] = bfx4_hi(w); } }
.LBB0_287:
	s_or_b64 exec, exec, s[68:69]
	s_ashr_i32 s17, s53, 4
	v_lshl_or_b32 v154, s16, 8, v191
	s_mul_hi_i32 s26, s17, 0x6000
	s_mulk_i32 s17, 0x6000
	s_add_u32 s62, s56, s17
	v_ashrrev_i32_e32 v155, 31, v154
	s_addc_u32 s63, s96, s26
	v_lshlrev_b64 v[146:147], 2, v[154:155]
	s_waitcnt vmcnt(0) lgkmcnt(0)
	s_barrier
	v_lshl_add_u64 v[160:161], s[62:63], 0, v[146:147]
	v_lshl_add_u64 v[170:171], s[20:21], 0, v[146:147]
	global_load_dwordx4 v[138:141], v[160:161], off offset:16
	global_load_dwordx4 v[142:145], v[160:161], off
	global_load_dwordx4 v[196:199], v[170:171], off offset:16
	global_load_dwordx4 v[146:149], v[170:171], off
	v_lshlrev_b64 v[154:155], 1, v[154:155]
	s_waitcnt vmcnt(0)
	v_pk_mul_f32 v[150:151], v[144:145], v[148:149]
	v_pk_mul_f32 v[152:153], v[142:143], v[146:147]
	v_pk_mul_f32 v[146:147], v[140:141], v[198:199]
	v_pk_mul_f32 v[148:149], v[138:139], v[196:197]
	global_load_dwordx4 v[138:141], v[160:161], off offset:528
	global_load_dwordx4 v[196:199], v[160:161], off offset:512
	global_load_dwordx4 v[200:203], v[170:171], off offset:528
	global_load_dwordx4 v[204:207], v[170:171], off offset:512
	v_add_u32_e32 v170, s15, v167
	v_ashrrev_i32_e32 v171, 31, v170
	v_lshlrev_b64 v[170:171], 11, v[170:171]
	v_lshl_add_u64 v[170:171], s[78:79], 0, v[170:171]
	v_lshl_add_u64 v[170:171], v[170:171], 0, v[154:155]
	ds_read_b32 v160, v175
	s_waitcnt vmcnt(1)
	v_pk_mul_f32 v[140:141], v[140:141], v[202:203]
	s_waitcnt vmcnt(0)
	v_pk_mul_f32 v[142:143], v[198:199], v[206:207]
	v_pk_mul_f32 v[144:145], v[196:197], v[204:205]
	v_pk_mul_f32 v[138:139], v[138:139], v[200:201]
	s_waitcnt lgkmcnt(0)
	v_pk_mul_f32 v[202:203], v[126:127], v[160:161] op_sel_hi:[1,0]
	v_pk_mul_f32 v[204:205], v[124:125], v[160:161] op_sel_hi:[1,0]
	v_pk_mul_f32 v[206:207], v[120:121], v[160:161] op_sel_hi:[1,0]
	s_waitcnt vmcnt(0)
	s_nop 1
	v_mov_b32_e32 v196, v224
	v_mov_b32_e32 v197, v225
	v_mov_b32_e32 v198, v226
	v_mov_b32_e32 v199, v227
	v_lshlrev_b32_e32 v200, 16, v196
	v_and_b32_e32 v201, 0xffff0000, v196
	v_lshlrev_b32_e32 v196, 16, v197
	v_and_b32_e32 v197, 0xffff0000, v197
	v_pk_fma_f32 v[202:203], v[150:151], v[202:203], v[196:197]
	v_pk_fma_f32 v[196:197], v[152:153], v[204:205], v[200:201]
	v_lshlrev_b32_e32 v200, 16, v198
	v_and_b32_e32 v201, 0xffff0000, v198
	v_lshlrev_b32_e32 v198, 16, v199
	v_and_b32_e32 v199, 0xffff0000, v199
	v_pk_mul_f32 v[204:205], v[122:123], v[160:161] op_sel_hi:[1,0]
	v_cvt_pk_bf16_f32 v196, v196, v197
	v_pk_fma_f32 v[204:205], v[146:147], v[204:205], v[198:199]
	v_pk_fma_f32 v[198:199], v[148:149], v[206:207], v[200:201]
	v_cvt_pk_bf16_f32 v197, v202, v203
	v_cvt_pk_bf16_f32 v198, v198, v199
	v_cvt_pk_bf16_f32 v199, v204, v205
	global_store_dwordx4 v[170:171], v[196:199], off
	v_pk_mul_f32 v[202:203], v[106:107], v[160:161] op_sel_hi:[1,0]
	v_pk_mul_f32 v[204:205], v[104:105], v[160:161] op_sel_hi:[1,0]
	s_nop 1
	v_mov_b32_e32 v196, v228
	v_mov_b32_e32 v197, v229
	v_mov_b32_e32 v198, v230
	v_mov_b32_e32 v199, v231
	v_lshlrev_b32_e32 v200, 16, v196
	v_and_b32_e32 v201, 0xffff0000, v196
	v_lshlrev_b32_e32 v196, 16, v197
	v_and_b32_e32 v197, 0xffff0000, v197
	v_pk_fma_f32 v[202:203], v[142:143], v[202:203], v[196:197]
	v_pk_fma_f32 v[196:197], v[144:145], v[204:205], v[200:201]
	v_lshlrev_b32_e32 v200, 16, v198
	v_and_b32_e32 v201, 0xffff0000, v198
	v_lshlrev_b32_e32 v198, 16, v199
	v_and_b32_e32 v199, 0xffff0000, v199
	v_pk_mul_f32 v[204:205], v[98:99], v[160:161] op_sel_hi:[1,0]
	v_pk_mul_f32 v[160:161], v[96:97], v[160:161] op_sel_hi:[1,0]
	v_pk_fma_f32 v[204:205], v[140:141], v[204:205], v[198:199]
	v_pk_fma_f32 v[160:161], v[138:139], v[160:161], v[200:201]
	v_cvt_pk_bf16_f32 v196, v196, v197
	v_cvt_pk_bf16_f32 v197, v202, v203
	v_cvt_pk_bf16_f32 v198, v160, v161
	v_cvt_pk_bf16_f32 v199, v204, v205
	global_store_dwordx4 v[170:171], v[196:199], off offset:256
	v_lshlrev_b32_e32 v217, 11, v180
	v_lshl_add_u32 v217, v191, 1, v217
	global_load_dwordx4 v[120:123], v217, s[34:35] offset:256
	v_lshlrev_b32_e32 v217, 11, v182
	v_lshl_add_u32 v217, v191, 1, v217
	global_load_dwordx4 v[124:127], v217, s[34:35]
	global_load_dwordx4 v[96:99], v217, s[34:35] offset:256
	v_lshlrev_b32_e32 v217, 11, v184
	v_lshl_add_u32 v217, v191, 1, v217
	global_load_dwordx4 v[104:107], v217, s[34:35]
	v_add_u32_e32 v170, s15, v176
	v_ashrrev_i32_e32 v171, 31, v170
	v_lshlrev_b64 v[170:171], 11, v[170:171]
	v_lshl_add_u64 v[170:171], s[78:79], 0, v[170:171]
	v_lshl_add_u64 v[170:171], v[170:171], 0, v[154:155]
	ds_read_b32 v160, v177
	s_waitcnt lgkmcnt(0)
; __device__ __forceinline__ unsigned cvt_pk_bf16(float lo, float hi) { const f32x2 v = (f32x2){lo, hi}; return __builtin_bit_cast(unsigned, __builtin_convertvector(v, bf16v2)); }
; __device__ __forceinline__ f32x4 bfx4_lo(u32x4 w) { return (f32x4){bf_lo(w.x), bf_hi(w.x), bf_lo(w.y), bf_hi(w.y)}; }
; __device__ __forceinline__ f32x4 bfx4_hi(u32x4 w) { return (f32x4){bf_lo(w.z), bf_hi(w.z), bf_lo(w.w), bf_hi(w.w)}; }
; __device__ __forceinline__ void fused_epi(f32x4 (&acc)[2][2][4][2], const Unit& u, int wr, int wc, int fr, int fq, LAS unsigned char* xl, int wid, int lane, const FuseArgs& f) {
;     ...
;             for (int m = 0; m < 4; ++m) { const int r = ai * HALF + wr * 64 + m * 16 + fr; const float rstd = S[r];
; #pragma unroll
;                 for (int bj = 0; bj < 2; ++bj) { const size_t off = (size_t)(pm * BM + r) * DM + colb + bj * HALF;
;                     const u32x4 xw = *(const u32x4*)((const bf16_t*)(f.ws + WS_XR) + off);
;                     const f32x4 x0 = bfx4_lo(xw) + Gv[bj][0] * (acc[ai][bj][m][0] * rstd), x1 = bfx4_hi(xw) + Gv[bj][1] * (acc[ai][bj][m][1] * rstd);
;                     if (f.out_f32) { *(f32x4*)(f.xoutf + off) = x0; *(f32x4*)(f.xoutf + off + 4) = x1; acc[ai][bj][m][0] = x0; acc[ai][bj][m][1] = x1; }
;                     else { u32x4 w; w.x = cvt_pk_bf16(x0[0], x0[1]); w.y = cvt_pk_bf16(x0[2], x0[3]); w.z = cvt_pk_bf16(x1[0], x1[1]); w.w = cvt_pk_bf16(x1[2], x1[3]);
;                         *(u32x4*)((bf16_t*)(f.ws + WS_XR) + off) = w; acc[ai][bj][m][0] = bfx4_lo(w); acc[ai][bj][m][1] = bfx4_hi(w); } }
	v_pk_mul_f32 v[202:203], v[118:119], v[160:161] op_sel_hi:[1,0]
	v_pk_mul_f32 v[204:205], v[116:117], v[160:161] op_sel_hi:[1,0]
	v_pk_mul_f32 v[206:207], v[112:113], v[160:161] op_sel_hi:[1,0]
	s_nop 1
	v_mov_b32_e32 v196, v232
	v_mov_b32_e32 v197, v233
	v_mov_b32_e32 v198, v234
	v_mov_b32_e32 v199, v235
	v_lshlrev_b32_e32 v200, 16, v196
	v_and_b32_e32 v201, 0xffff0000, v196
	v_lshlrev_b32_e32 v196, 16, v197
	v_and_b32_e32 v197, 0xffff0000, v197
	v_pk_fma_f32 v[202:203], v[150:151], v[202:203], v[196:197]
	v_pk_fma_f32 v[196:197], v[152:153], v[204:205], v[200:201]
	v_lshlrev_b32_e32 v200, 16, v198
	v_and_b32_e32 v201, 0xffff0000, v198
	v_lshlrev_b32_e32 v198, 16, v199
	v_and_b32_e32 v199, 0xffff0000, v199
	v_pk_mul_f32 v[204:205], v[114:115], v[160:161] op_sel_hi:[1,0]
	v_cvt_pk_bf16_f32 v196, v196, v197
	v_pk_fma_f32 v[204:205], v[146:147], v[204:205], v[198:199]
	v_pk_fma_f32 v[198:199], v[148:149], v[206:207], v[200:201]
	v_cvt_pk_bf16_f32 v197, v202, v203
	v_cvt_pk_bf16_f32 v198, v198, v199
	v_cvt_pk_bf16_f32 v199, v204, v205
	global_store_dwordx4 v[170:171], v[196:199], off
	v_pk_mul_f32 v[202:203], v[90:91], v[160:161] op_sel_hi:[1,0]
	v_pk_mul_f32 v[204:205], v[88:89], v[160:161] op_sel_hi:[1,0]
	s_nop 1
	v_mov_b32_e32 v196, v236
	v_mov_b32_e32 v197, v237
	v_mov_b32_e32 v198, v238
	v_mov_b32_e32 v199, v239
	v_lshlrev_b32_e32 v200, 16, v196
	v_and_b32_e32 v201, 0xffff0000, v196
	v_lshlrev_b32_e32 v196, 16, v197
	v_and_b32_e32 v197, 0xffff0000, v197
	v_pk_fma_f32 v[202:203], v[142:143], v[202:203], v[196:197]
	v_pk_fma_f32 v[196:197], v[144:145], v[204:205], v[200:201]
	v_lshlrev_b32_e32 v200, 16, v198
	v_and_b32_e32 v201, 0xffff0000, v198
	v_lshlrev_b32_e32 v198, 16, v199
	v_and_b32_e32 v199, 0xffff0000, v199
	v_pk_mul_f32 v[204:205], v[82:83], v[160:161] op_sel_hi:[1,0]
	v_pk_mul_f32 v[160:161], v[80:81], v[160:161] op_sel_hi:[1,0]
	v_pk_fma_f32 v[204:205], v[140:141], v[204:205], v[198:199]
	v_pk_fma_f32 v[160:161], v[138:139], v[160:161], v[200:201]
	v_cvt_pk_bf16_f32 v196, v196, v197
	v_cvt_pk_bf16_f32 v197, v202, v203
	v_cvt_pk_bf16_f32 v198, v160, v161
	v_cvt_pk_bf16_f32 v199, v204, v205
	global_store_dwordx4 v[170:171], v[196:199], off offset:256
	v_lshlrev_b32_e32 v217, 11, v184
	v_lshl_add_u32 v217, v191, 1, v217
	global_load_dwordx4 v[112:115], v217, s[34:35] offset:256
	v_lshlrev_b32_e32 v217, 11, v186
	v_lshl_add_u32 v217, v191, 1, v217
	global_load_dwordx4 v[116:119], v217, s[34:35]
	global_load_dwordx4 v[88:91], v217, s[34:35] offset:256
	v_lshlrev_b32_e32 v217, 11, v188
	v_lshl_add_u32 v217, v191, 1, v217
	global_load_dwordx4 v[80:83], v217, s[34:35]
	v_add_u32_e32 v170, s15, v178
	v_ashrrev_i32_e32 v171, 31, v170
	v_lshlrev_b64 v[170:171], 11, v[170:171]
	v_lshl_add_u64 v[170:171], s[78:79], 0, v[170:171]
	v_lshl_add_u64 v[170:171], v[170:171], 0, v[154:155]
	ds_read_b32 v160, v179
	s_waitcnt lgkmcnt(0)
	v_pk_mul_f32 v[202:203], v[110:111], v[160:161] op_sel_hi:[1,0]
	v_pk_mul_f32 v[204:205], v[108:109], v[160:161] op_sel_hi:[1,0]
	v_pk_mul_f32 v[206:207], v[100:101], v[160:161] op_sel_hi:[1,0]
	s_nop 1
	v_mov_b32_e32 v196, v240
	v_mov_b32_e32 v197, v241
	v_mov_b32_e32 v198, v242
	v_mov_b32_e32 v199, v243
	v_lshlrev_b32_e32 v200, 16, v196
	v_and_b32_e32 v201, 0xffff0000, v196
	v_lshlrev_b32_e32 v196, 16, v197
	v_and_b32_e32 v197, 0xffff0000, v197
	v_pk_fma_f32 v[202:203], v[150:151], v[202:203], v[196:197]
	v_pk_fma_f32 v[196:197], v[152:153], v[204:205], v[200:201]
	v_lshlrev_b32_e32 v200, 16, v198
	v_and_b32_e32 v201, 0xffff0000, v198
	v_lshlrev_b32_e32 v198, 16, v199
	v_and_b32_e32 v199, 0xffff0000, v199
	v_pk_mul_f32 v[204:205], v[102:103], v[160:161] op_sel_hi:[1,0]
	v_cvt_pk_bf16_f32 v196, v196, v197
	v_pk_fma_f32 v[204:205], v[146:147], v[204:205], v[198:199]
	v_pk_fma_f32 v[198:199], v[148:149], v[206:207], v[200:201]
	v_cvt_pk_bf16_f32 v197, v202, v203
	v_cvt_pk_bf16_f32 v198, v198, v199
	v_cvt_pk_bf16_f32 v199, v204, v205
	global_store_dwordx4 v[170:171], v[196:199], off
	v_pk_mul_f32 v[202:203], v[78:79], v[160:161] op_sel_hi:[1,0]
	v_pk_mul_f32 v[204:205], v[76:77], v[160:161] op_sel_hi:[1,0]
	s_nop 1
	v_mov_b32_e32 v196, v244
	v_mov_b32_e32 v197, v245
	v_mov_b32_e32 v198, v246
	v_mov_b32_e32 v199, v247
	v_lshlrev_b32_e32 v200, 16, v196
	v_and_b32_e32 v201, 0xffff0000, v196
	v_lshlrev_b32_e32 v196, 16, v197
	v_and_b32_e32 v197, 0xffff0000, v197
	v_pk_fma_f32 v[202:203], v[142:143], v[202:203], v[196:197]
	v_pk_fma_f32 v[196:197], v[144:145], v[204:205], v[200:201]
	v_lshlrev_b32_e32 v200, 16, v198
	v_and_b32_e32 v201, 0xffff0000, v198
	v_lshlrev_b32_e32 v198, 16, v199
	v_and_b32_e32 v199, 0xffff0000, v199
	v_pk_mul_f32 v[204:205], v[74:75], v[160:161] op_sel_hi:[1,0]
	v_pk_mul_f32 v[160:161], v[72:73], v[160:161] op_sel_hi:[1,0]
	v_pk_fma_f32 v[204:205], v[140:141], v[204:205], v[198:199]
	v_pk_fma_f32 v[160:161], v[138:139], v[160:161], v[200:201]
	v_cvt_pk_bf16_f32 v196, v196, v197
	v_cvt_pk_bf16_f32 v197, v202, v203
	v_cvt_pk_bf16_f32 v198, v160, v161
	v_cvt_pk_bf16_f32 v199, v204, v205
	global_store_dwordx4 v[170:171], v[196:199], off offset:256
	v_lshlrev_b32_e32 v217, 11, v188
	v_lshl_add_u32 v217, v191, 1, v217
	global_load_dwordx4 v[108:111], v217, s[34:35] offset:256
	v_add_u32_e32 v170, s15, v180
	v_ashrrev_i32_e32 v171, 31, v170
	v_lshlrev_b64 v[170:171], 11, v[170:171]
	v_lshl_add_u64 v[170:171], s[78:79], 0, v[170:171]
	v_lshl_add_u64 v[170:171], v[170:171], 0, v[154:155]
	ds_read_b32 v160, v181
	s_waitcnt lgkmcnt(0)
; __device__ __forceinline__ unsigned cvt_pk_bf16(float lo, float hi) { const f32x2 v = (f32x2){lo, hi}; return __builtin_bit_cast(unsigned, __builtin_convertvector(v, bf16v2)); }
; __device__ __forceinline__ f32x4 bfx4_lo(u32x4 w) { return (f32x4){bf_lo(w.x), bf_hi(w.x), bf_lo(w.y), bf_hi(w.y)}; }
; __device__ __forceinline__ f32x4 bfx4_hi(u32x4 w) { return (f32x4){bf_lo(w.z), bf_hi(w.z), bf_lo(w.w), bf_hi(w.w)}; }
; __device__ __forceinline__ void fused_epi(f32x4 (&acc)[2][2][4][2], const Unit& u, int wr, int wc, int fr, int fq, LAS unsigned char* xl, int wid, int lane, const FuseArgs& f) {
;     ...
;             for (int m = 0; m < 4; ++m) { const int r = ai * HALF + wr * 64 + m * 16 + fr; const float rstd = S[r];
; #pragma unroll
;                 for (int bj = 0; bj < 2; ++bj) { const size_t off = (size_t)(pm * BM + r) * DM + colb + bj * HALF;
;                     const u32x4 xw = *(const u32x4*)((const bf16_t*)(f.ws + WS_XR) + off);
;                     const f32x4 x0 = bfx4_lo(xw) + Gv[bj][0] * (acc[ai][bj][m][0] * rstd), x1 = bfx4_hi(xw) + Gv[bj][1] * (acc[ai][bj][m][1] * rstd);
;                     if (f.out_f32) { *(f32x4*)(f.xoutf + off) = x0; *(f32x4*)(f.xoutf + off + 4) = x1; acc[ai][bj][m][0] = x0; acc[ai][bj][m][1] = x1; }
;                     else { u32x4 w; w.x = cvt_pk_bf16(x0[0], x0[1]); w.y = cvt_pk_bf16(x0[2], x0[3]); w.z = cvt_pk_bf16(x1[0], x1[1]); w.w = cvt_pk_bf16(x1[2], x1[3]);
;                         *(u32x4*)((bf16_t*)(f.ws + WS_XR) + off) = w; acc[ai][bj][m][0] = bfx4_lo(w); acc[ai][bj][m][1] = bfx4_hi(w); } }
	v_pk_mul_f32 v[202:203], v[94:95], v[160:161] op_sel_hi:[1,0]
	v_pk_mul_f32 v[204:205], v[92:93], v[160:161] op_sel_hi:[1,0]
	v_pk_mul_f32 v[206:207], v[84:85], v[160:161] op_sel_hi:[1,0]
	s_nop 1
	v_mov_b32_e32 v196, v248
	v_mov_b32_e32 v197, v249
	v_mov_b32_e32 v198, v250
	v_mov_b32_e32 v199, v251
	v_lshlrev_b32_e32 v200, 16, v196
	v_and_b32_e32 v201, 0xffff0000, v196
	v_lshlrev_b32_e32 v196, 16, v197
	v_and_b32_e32 v197, 0xffff0000, v197
	v_pk_fma_f32 v[202:203], v[150:151], v[202:203], v[196:197]
	v_pk_fma_f32 v[196:197], v[152:153], v[204:205], v[200:201]
	v_lshlrev_b32_e32 v200, 16, v198
	v_and_b32_e32 v201, 0xffff0000, v198
	v_lshlrev_b32_e32 v198, 16, v199
	v_and_b32_e32 v199, 0xffff0000, v199
	v_pk_mul_f32 v[204:205], v[86:87], v[160:161] op_sel_hi:[1,0]
	v_cvt_pk_bf16_f32 v196, v196, v197
	v_pk_fma_f32 v[204:205], v[146:147], v[204:205], v[198:199]
	v_pk_fma_f32 v[198:199], v[148:149], v[206:207], v[200:201]
	v_cvt_pk_bf16_f32 v197, v202, v203
	v_cvt_pk_bf16_f32 v198, v198, v199
	v_cvt_pk_bf16_f32 v199, v204, v205
	global_store_dwordx4 v[170:171], v[196:199], off
	v_pk_mul_f32 v[202:203], v[70:71], v[160:161] op_sel_hi:[1,0]
	v_pk_mul_f32 v[204:205], v[68:69], v[160:161] op_sel_hi:[1,0]
	s_waitcnt vmcnt(13)
	s_nop 1
	v_mov_b32_e32 v196, v120
	v_mov_b32_e32 v197, v121
	v_mov_b32_e32 v198, v122
	v_mov_b32_e32 v199, v123
	v_lshlrev_b32_e32 v200, 16, v196
	v_and_b32_e32 v201, 0xffff0000, v196
	v_lshlrev_b32_e32 v196, 16, v197
	v_and_b32_e32 v197, 0xffff0000, v197
	v_pk_fma_f32 v[202:203], v[142:143], v[202:203], v[196:197]
	v_pk_fma_f32 v[196:197], v[144:145], v[204:205], v[200:201]
	v_lshlrev_b32_e32 v200, 16, v198
	v_and_b32_e32 v201, 0xffff0000, v198
	v_lshlrev_b32_e32 v198, 16, v199
	v_and_b32_e32 v199, 0xffff0000, v199
	v_pk_mul_f32 v[204:205], v[66:67], v[160:161] op_sel_hi:[1,0]
	v_pk_mul_f32 v[160:161], v[64:65], v[160:161] op_sel_hi:[1,0]
	v_pk_fma_f32 v[204:205], v[140:141], v[204:205], v[198:199]
	v_pk_fma_f32 v[160:161], v[138:139], v[160:161], v[200:201]
	v_cvt_pk_bf16_f32 v196, v196, v197
	v_cvt_pk_bf16_f32 v197, v202, v203
	v_cvt_pk_bf16_f32 v198, v160, v161
	v_cvt_pk_bf16_f32 v199, v204, v205
	global_store_dwordx4 v[170:171], v[196:199], off offset:256
	v_add_u32_e32 v170, s15, v182
	v_ashrrev_i32_e32 v171, 31, v170
	v_lshlrev_b64 v[170:171], 11, v[170:171]
	v_lshl_add_u64 v[170:171], s[78:79], 0, v[170:171]
	v_lshl_add_u64 v[170:171], v[170:171], 0, v[154:155]
	ds_read_b32 v160, v183
	s_waitcnt lgkmcnt(0)
	v_pk_mul_f32 v[202:203], v[62:63], v[160:161] op_sel_hi:[1,0]
	v_pk_mul_f32 v[204:205], v[60:61], v[160:161] op_sel_hi:[1,0]
	v_pk_mul_f32 v[206:207], v[56:57], v[160:161] op_sel_hi:[1,0]
	s_waitcnt vmcnt(13)
	s_nop 1
	v_mov_b32_e32 v196, v124
	v_mov_b32_e32 v197, v125
	v_mov_b32_e32 v198, v126
	v_mov_b32_e32 v199, v127
	v_lshlrev_b32_e32 v200, 16, v196
	v_and_b32_e32 v201, 0xffff0000, v196
	v_lshlrev_b32_e32 v196, 16, v197
	v_and_b32_e32 v197, 0xffff0000, v197
	v_pk_fma_f32 v[202:203], v[150:151], v[202:203], v[196:197]
	v_pk_fma_f32 v[196:197], v[152:153], v[204:205], v[200:201]
	v_lshlrev_b32_e32 v200, 16, v198
	v_and_b32_e32 v201, 0xffff0000, v198
	v_lshlrev_b32_e32 v198, 16, v199
	v_and_b32_e32 v199, 0xffff0000, v199
	v_pk_mul_f32 v[204:205], v[58:59], v[160:161] op_sel_hi:[1,0]
	v_cvt_pk_bf16_f32 v196, v196, v197
	v_pk_fma_f32 v[204:205], v[146:147], v[204:205], v[198:199]
	v_pk_fma_f32 v[198:199], v[148:149], v[206:207], v[200:201]
	v_cvt_pk_bf16_f32 v197, v202, v203
	v_cvt_pk_bf16_f32 v198, v198, v199
	v_cvt_pk_bf16_f32 v199, v204, v205
	global_store_dwordx4 v[170:171], v[196:199], off
	v_pk_mul_f32 v[202:203], v[46:47], v[160:161] op_sel_hi:[1,0]
	v_pk_mul_f32 v[204:205], v[44:45], v[160:161] op_sel_hi:[1,0]
	s_waitcnt vmcnt(13)
	s_nop 1
	v_mov_b32_e32 v196, v96
	v_mov_b32_e32 v197, v97
	v_mov_b32_e32 v198, v98
	v_mov_b32_e32 v199, v99
	v_lshlrev_b32_e32 v200, 16, v196
	v_and_b32_e32 v201, 0xffff0000, v196
	v_lshlrev_b32_e32 v196, 16, v197
	v_and_b32_e32 v197, 0xffff0000, v197
	v_pk_fma_f32 v[202:203], v[142:143], v[202:203], v[196:197]
	v_pk_fma_f32 v[196:197], v[144:145], v[204:205], v[200:201]
	v_lshlrev_b32_e32 v200, 16, v198
	v_and_b32_e32 v201, 0xffff0000, v198
	v_lshlrev_b32_e32 v198, 16, v199
	v_and_b32_e32 v199, 0xffff0000, v199
	v_pk_mul_f32 v[204:205], v[38:39], v[160:161] op_sel_hi:[1,0]
	v_pk_mul_f32 v[160:161], v[36:37], v[160:161] op_sel_hi:[1,0]
	v_pk_fma_f32 v[204:205], v[140:141], v[204:205], v[198:199]
	v_pk_fma_f32 v[160:161], v[138:139], v[160:161], v[200:201]
	v_cvt_pk_bf16_f32 v196, v196, v197
	v_cvt_pk_bf16_f32 v197, v202, v203
	v_cvt_pk_bf16_f32 v198, v160, v161
	v_cvt_pk_bf16_f32 v199, v204, v205
	global_store_dwordx4 v[170:171], v[196:199], off offset:256
	v_add_u32_e32 v170, s15, v184
	v_ashrrev_i32_e32 v171, 31, v170
	v_lshlrev_b64 v[170:171], 11, v[170:171]
	v_lshl_add_u64 v[170:171], s[78:79], 0, v[170:171]
	v_lshl_add_u64 v[170:171], v[170:171], 0, v[154:155]
	ds_read_b32 v160, v185
	s_waitcnt lgkmcnt(0)
	v_pk_mul_f32 v[202:203], v[54:55], v[160:161] op_sel_hi:[1,0]
	v_pk_mul_f32 v[204:205], v[52:53], v[160:161] op_sel_hi:[1,0]
	v_pk_mul_f32 v[206:207], v[48:49], v[160:161] op_sel_hi:[1,0]
	s_waitcnt vmcnt(13)
; __device__ __forceinline__ unsigned cvt_pk_bf16(float lo, float hi) { const f32x2 v = (f32x2){lo, hi}; return __builtin_bit_cast(unsigned, __builtin_convertvector(v, bf16v2)); }
; __device__ __forceinline__ f32x4 bfx4_lo(u32x4 w) { return (f32x4){bf_lo(w.x), bf_hi(w.x), bf_lo(w.y), bf_hi(w.y)}; }
; __device__ __forceinline__ f32x4 bfx4_hi(u32x4 w) { return (f32x4){bf_lo(w.z), bf_hi(w.z), bf_lo(w.w), bf_hi(w.w)}; }
; __device__ __forceinline__ void fused_epi(f32x4 (&acc)[2][2][4][2], const Unit& u, int wr, int wc, int fr, int fq, LAS unsigned char* xl, int wid, int lane, const FuseArgs& f) {
;     ...
;             for (int m = 0; m < 4; ++m) { const int r = ai * HALF + wr * 64 + m * 16 + fr; const float rstd = S[r];
; #pragma unroll
;                 for (int bj = 0; bj < 2; ++bj) { const size_t off = (size_t)(pm * BM + r) * DM + colb + bj * HALF;
;                     const u32x4 xw = *(const u32x4*)((const bf16_t*)(f.ws + WS_XR) + off);
;                     const f32x4 x0 = bfx4_lo(xw) + Gv[bj][0] * (acc[ai][bj][m][0] * rstd), x1 = bfx4_hi(xw) + Gv[bj][1] * (acc[ai][bj][m][1] * rstd);
;                     if (f.out_f32) { *(f32x4*)(f.xoutf + off) = x0; *(f32x4*)(f.xoutf + off + 4) = x1; acc[ai][bj][m][0] = x0; acc[ai][bj][m][1] = x1; }
;                     else { u32x4 w; w.x = cvt_pk_bf16(x0[0], x0[1]); w.y = cvt_pk_bf16(x0[2], x0[3]); w.z = cvt_pk_bf16(x1[0], x1[1]); w.w = cvt_pk_bf16(x1[2], x1[3]);
;                         *(u32x4*)((bf16_t*)(f.ws + WS_XR) + off) = w; acc[ai][bj][m][0] = bfx4_lo(w); acc[ai][bj][m][1] = bfx4_hi(w); } }
	s_nop 1
	v_mov_b32_e32 v196, v104
	v_mov_b32_e32 v197, v105
	v_mov_b32_e32 v198, v106
	v_mov_b32_e32 v199, v107
	v_lshlrev_b32_e32 v200, 16, v196
	v_and_b32_e32 v201, 0xffff0000, v196
	v_lshlrev_b32_e32 v196, 16, v197
	v_and_b32_e32 v197, 0xffff0000, v197
	v_pk_fma_f32 v[202:203], v[150:151], v[202:203], v[196:197]
	v_pk_fma_f32 v[196:197], v[152:153], v[204:205], v[200:201]
	v_lshlrev_b32_e32 v200, 16, v198
	v_and_b32_e32 v201, 0xffff0000, v198
	v_lshlrev_b32_e32 v198, 16, v199
	v_and_b32_e32 v199, 0xffff0000, v199
	v_pk_mul_f32 v[204:205], v[50:51], v[160:161] op_sel_hi:[1,0]
	v_cvt_pk_bf16_f32 v196, v196, v197
	v_pk_fma_f32 v[204:205], v[146:147], v[204:205], v[198:199]
	v_pk_fma_f32 v[198:199], v[148:149], v[206:207], v[200:201]
	v_cvt_pk_bf16_f32 v197, v202, v203
	v_cvt_pk_bf16_f32 v198, v198, v199
	v_cvt_pk_bf16_f32 v199, v204, v205
	global_store_dwordx4 v[170:171], v[196:199], off
	v_pk_mul_f32 v[202:203], v[30:31], v[160:161] op_sel_hi:[1,0]
	v_pk_mul_f32 v[204:205], v[28:29], v[160:161] op_sel_hi:[1,0]
	s_waitcnt vmcnt(11)
	s_nop 1
	v_mov_b32_e32 v196, v112
	v_mov_b32_e32 v197, v113
	v_mov_b32_e32 v198, v114
	v_mov_b32_e32 v199, v115
	v_lshlrev_b32_e32 v200, 16, v196
	v_and_b32_e32 v201, 0xffff0000, v196
	v_lshlrev_b32_e32 v196, 16, v197
	v_and_b32_e32 v197, 0xffff0000, v197
	v_pk_fma_f32 v[202:203], v[142:143], v[202:203], v[196:197]
	v_pk_fma_f32 v[196:197], v[144:145], v[204:205], v[200:201]
	v_lshlrev_b32_e32 v200, 16, v198
	v_and_b32_e32 v201, 0xffff0000, v198
	v_lshlrev_b32_e32 v198, 16, v199
	v_and_b32_e32 v199, 0xffff0000, v199
	v_pk_mul_f32 v[204:205], v[22:23], v[160:161] op_sel_hi:[1,0]
	v_pk_mul_f32 v[160:161], v[20:21], v[160:161] op_sel_hi:[1,0]
	v_pk_fma_f32 v[204:205], v[140:141], v[204:205], v[198:199]
	v_pk_fma_f32 v[160:161], v[138:139], v[160:161], v[200:201]
	v_cvt_pk_bf16_f32 v196, v196, v197
	v_cvt_pk_bf16_f32 v197, v202, v203
	v_cvt_pk_bf16_f32 v198, v160, v161
	v_cvt_pk_bf16_f32 v199, v204, v205
	global_store_dwordx4 v[170:171], v[196:199], off offset:256
	v_add_u32_e32 v170, s15, v186
	v_ashrrev_i32_e32 v171, 31, v170
	v_lshlrev_b64 v[170:171], 11, v[170:171]
	v_lshl_add_u64 v[170:171], s[78:79], 0, v[170:171]
	v_lshl_add_u64 v[170:171], v[170:171], 0, v[154:155]
	ds_read_b32 v160, v187
	s_waitcnt lgkmcnt(0)
	v_pk_mul_f32 v[202:203], v[42:43], v[160:161] op_sel_hi:[1,0]
	v_pk_mul_f32 v[204:205], v[40:41], v[160:161] op_sel_hi:[1,0]
	v_pk_mul_f32 v[206:207], v[32:33], v[160:161] op_sel_hi:[1,0]
	s_waitcnt vmcnt(11)
	s_nop 1
	v_mov_b32_e32 v196, v116
	v_mov_b32_e32 v197, v117
	v_mov_b32_e32 v198, v118
	v_mov_b32_e32 v199, v119
	v_lshlrev_b32_e32 v200, 16, v196
	v_and_b32_e32 v201, 0xffff0000, v196
	v_lshlrev_b32_e32 v196, 16, v197
	v_and_b32_e32 v197, 0xffff0000, v197
	v_pk_fma_f32 v[202:203], v[150:151], v[202:203], v[196:197]
	v_pk_fma_f32 v[196:197], v[152:153], v[204:205], v[200:201]
	v_lshlrev_b32_e32 v200, 16, v198
	v_and_b32_e32 v201, 0xffff0000, v198
	v_lshlrev_b32_e32 v198, 16, v199
	v_and_b32_e32 v199, 0xffff0000, v199
	v_pk_mul_f32 v[204:205], v[34:35], v[160:161] op_sel_hi:[1,0]
	v_cvt_pk_bf16_f32 v196, v196, v197
	v_pk_fma_f32 v[204:205], v[146:147], v[204:205], v[198:199]
	v_pk_fma_f32 v[198:199], v[148:149], v[206:207], v[200:201]
	v_cvt_pk_bf16_f32 v197, v202, v203
	v_cvt_pk_bf16_f32 v198, v198, v199
	v_cvt_pk_bf16_f32 v199, v204, v205
	global_store_dwordx4 v[170:171], v[196:199], off
	v_pk_mul_f32 v[202:203], v[14:15], v[160:161] op_sel_hi:[1,0]
	v_pk_mul_f32 v[204:205], v[12:13], v[160:161] op_sel_hi:[1,0]
	s_waitcnt vmcnt(11)
	s_nop 1
	v_mov_b32_e32 v196, v88
	v_mov_b32_e32 v197, v89
	v_mov_b32_e32 v198, v90
	v_mov_b32_e32 v199, v91
	v_lshlrev_b32_e32 v200, 16, v196
	v_and_b32_e32 v201, 0xffff0000, v196
	v_lshlrev_b32_e32 v196, 16, v197
	v_and_b32_e32 v197, 0xffff0000, v197
	v_pk_fma_f32 v[202:203], v[142:143], v[202:203], v[196:197]
	v_pk_fma_f32 v[196:197], v[144:145], v[204:205], v[200:201]
	v_lshlrev_b32_e32 v200, 16, v198
	v_and_b32_e32 v201, 0xffff0000, v198
	v_lshlrev_b32_e32 v198, 16, v199
	v_and_b32_e32 v199, 0xffff0000, v199
	v_pk_mul_f32 v[204:205], v[10:11], v[160:161] op_sel_hi:[1,0]
	v_pk_mul_f32 v[160:161], v[8:9], v[160:161] op_sel_hi:[1,0]
	v_pk_fma_f32 v[204:205], v[140:141], v[204:205], v[198:199]
	v_pk_fma_f32 v[160:161], v[138:139], v[160:161], v[200:201]
	v_cvt_pk_bf16_f32 v196, v196, v197
	v_cvt_pk_bf16_f32 v197, v202, v203
	v_cvt_pk_bf16_f32 v198, v160, v161
	v_cvt_pk_bf16_f32 v199, v204, v205
	global_store_dwordx4 v[170:171], v[196:199], off offset:256
	v_add_u32_e32 v170, s15, v188
	v_ashrrev_i32_e32 v171, 31, v170
	v_lshlrev_b64 v[170:171], 11, v[170:171]
	v_lshl_add_u64 v[170:171], s[78:79], 0, v[170:171]
	v_lshl_add_u64 v[154:155], v[170:171], 0, v[154:155]
	ds_read_b32 v160, v189
	s_waitcnt lgkmcnt(0)
	v_pk_mul_f32 v[200:201], v[26:27], v[160:161] op_sel_hi:[1,0]
	v_pk_mul_f32 v[202:203], v[24:25], v[160:161] op_sel_hi:[1,0]
	s_waitcnt vmcnt(11)
	s_nop 1
	v_mov_b32_e32 v196, v80
	v_mov_b32_e32 v197, v81
	v_mov_b32_e32 v198, v82
	v_mov_b32_e32 v199, v83
	v_lshlrev_b32_e32 v170, 16, v196
	v_and_b32_e32 v171, 0xffff0000, v196
	v_lshlrev_b32_e32 v196, 16, v197
	v_and_b32_e32 v197, 0xffff0000, v197
	v_pk_fma_f32 v[150:151], v[150:151], v[200:201], v[196:197]
	v_pk_fma_f32 v[152:153], v[152:153], v[202:203], v[170:171]
	v_lshlrev_b32_e32 v170, 16, v198
	v_and_b32_e32 v171, 0xffff0000, v198
	v_lshlrev_b32_e32 v196, 16, v199
	v_and_b32_e32 v197, 0xffff0000, v199
	v_pk_mul_f32 v[198:199], v[18:19], v[160:161] op_sel_hi:[1,0]
	v_pk_mul_f32 v[200:201], v[16:17], v[160:161] op_sel_hi:[1,0]
	v_pk_fma_f32 v[196:197], v[146:147], v[198:199], v[196:197]
	v_pk_fma_f32 v[148:149], v[148:149], v[200:201], v[170:171]
	v_cvt_pk_bf16_f32 v146, v152, v153
	v_cvt_pk_bf16_f32 v147, v150, v151
	v_cvt_pk_bf16_f32 v148, v148, v149
	v_cvt_pk_bf16_f32 v149, v196, v197
	global_store_dwordx4 v[154:155], v[146:149], off
	v_pk_mul_f32 v[152:153], v[6:7], v[160:161] op_sel_hi:[1,0]
	v_pk_mul_f32 v[170:171], v[4:5], v[160:161] op_sel_hi:[1,0]
	s_waitcnt vmcnt(9)
	s_nop 1
	v_mov_b32_e32 v146, v108
	v_mov_b32_e32 v147, v109
	v_mov_b32_e32 v148, v110
	v_mov_b32_e32 v149, v111
	v_lshlrev_b32_e32 v150, 16, v146
	v_and_b32_e32 v151, 0xffff0000, v146
	v_lshlrev_b32_e32 v146, 16, v147
	v_and_b32_e32 v147, 0xffff0000, v147
	v_pk_fma_f32 v[142:143], v[142:143], v[152:153], v[146:147]
	v_pk_fma_f32 v[144:145], v[144:145], v[170:171], v[150:151]
	v_lshlrev_b32_e32 v146, 16, v148
	v_and_b32_e32 v147, 0xffff0000, v148
	v_lshlrev_b32_e32 v148, 16, v149
	v_and_b32_e32 v149, 0xffff0000, v149
	v_pk_mul_f32 v[150:151], v[2:3], v[160:161] op_sel_hi:[1,0]
	v_pk_mul_f32 v[152:153], v[0:1], v[160:161] op_sel_hi:[1,0]
	v_pk_fma_f32 v[148:149], v[140:141], v[150:151], v[148:149]
	v_pk_fma_f32 v[140:141], v[138:139], v[152:153], v[146:147]
	v_cvt_pk_bf16_f32 v138, v144, v145
	v_cvt_pk_bf16_f32 v139, v142, v143
	v_cvt_pk_bf16_f32 v140, v140, v141
	v_cvt_pk_bf16_f32 v141, v148, v149
	global_store_dwordx4 v[154:155], v[138:141], off offset:256
	s_branch .LBB0_248
